# speedup vs baseline: 1.0089x; 1.0077x over previous
; #define PG8_STAGE(bufoff, gbase, voff) do { _Pragma("unroll") for (int _i = 0; _i < 2; ++_i) \
;         __builtin_amdgcn_global_load_lds((const unsigned*)((const char*)(gbase) + (voff)[_i]), (PG8_LAS unsigned*)(lds + (bufoff) + ldsw + _i * 8192), 16, 0, 0); } while (0)
; #define PG8_LDA(dst, b, h) do { _Pragma("unroll") for (int m = 0; m < 4; ++m) _Pragma("unroll") for (int k = 0; k < 2; ++k) dst[m][k] = *(const PG8_LAS bf16x8*)(lds + PG8_SA(b, h) + aoff + m * 2048 + k * 1024); } while (0)
; #define PG8_LDB(dst, b, h) do { _Pragma("unroll") for (int n = 0; n < 2; ++n) _Pragma("unroll") for (int k = 0; k < 2; ++k) dst[n][k] = *(const PG8_LAS bf16x8*)(lds + PG8_SB(b, h) + boff + n * 2048 + k * 1024); } while (0)
; #define PG8_MMA(ai, bj, At, Bt) do { __builtin_amdgcn_s_setprio(1); _Pragma("unroll") for (int m = 0; m < 4; ++m) _Pragma("unroll") for (int n = 0; n < 2; ++n) _Pragma("unroll") for (int k = 0; k < 2; ++k) \
;         acc[ai][bj][m][n] = __builtin_amdgcn_mfma_f32_16x16x32_bf16(Bt[n][k], At[m][k], acc[ai][bj][m][n], 0, 0, 0); __builtin_amdgcn_s_setprio(0); } while (0)
; #define PG8_WAIT_V(n) asm volatile("s_waitcnt vmcnt(" #n ")" ::: "memory")
; #define PG8_WAIT_L(n) asm volatile("s_waitcnt lgkmcnt(" #n ")" ::: "memory")
; #define PG8_BAR __builtin_amdgcn_s_barrier()
; #define PG8_SCHED __builtin_amdgcn_sched_barrier(0)
; template <class Epi, class Sched, bool ALIGN_EPI = false, bool SP2 = false>
; __device__ __forceinline__ void gemm_phase(PG8_LAS unsigned char* lds, const Gemm g, const Sched& S, const Epi& E) {
;     ...
;             PG8_LDB(B0, 0, 0); PG8_LDB(B1, 0, 1); PG8_SCHED; PG8_LDA(At, 0, 0); PG8_STAGE(PG8_SA(1, 1), a1 + hstep, voffA);
;             PG8_WAIT_V(8); PG8_WAIT_L(0); PG8_BAR; PG8_MMA(0, 0, At, B0); PG8_MMA(0, 1, At, B1); PG8_BAR; PG8_SCHED;
;             PG8_LDA(At, 0, 1); PG8_STAGE(PG8_SB(0, 0), b2, voffB); PG8_STAGE(PG8_SB(0, 1), b2 + hstep, voffB); PG8_STAGE(PG8_SA(0, 0), a2, voffA);
;             PG8_WAIT_V(8); PG8_WAIT_L(0); PG8_BAR; PG8_MMA(1, 0, At, B0); PG8_MMA(1, 1, At, B1); PG8_BAR; PG8_SCHED;
.LBB0_205:
	s_add_u32 s36, s68, 0xfff80080
	s_addc_u32 s37, s69, -1
	s_add_i32 s38, 0, 0x10000
	s_cmp_eq_u32 s89, 28
	s_cselect_b32 s73, s9, s37
	s_cselect_b32 s72, s61, s36
	s_cselect_b32 s71, s59, s88
	s_cselect_b32 s70, s87, s3
	s_add_i32 s39, 0, 0x14000
	ds_read_b128 v[80:83], v204
	ds_read_b128 v[88:91], v204 offset:1024
	ds_read_b128 v[104:107], v204 offset:2048
	ds_read_b128 v[108:111], v204 offset:3072
	ds_read_b128 v[128:131], v204 offset:16384
	ds_read_b128 v[132:135], v204 offset:17408
	ds_read_b128 v[152:155], v204 offset:18432
	ds_read_b128 v[156:159], v204 offset:19456
	s_add_i32 m0, s67, 0xc000
	ds_read_b128 v[160:163], v240
	ds_read_b128 v[164:167], v240 offset:1024
	ds_read_b128 v[168:171], v240 offset:2048
	ds_read_b128 v[172:175], v240 offset:3072
	ds_read_b128 v[176:179], v240 offset:4096
	ds_read_b128 v[180:183], v240 offset:5120
	ds_read_b128 v[184:187], v240 offset:6144
	ds_read_b128 v[200:203], v240 offset:7168
	global_load_lds_dwordx4 v196, s[68:69]
	s_add_i32 m0, s67, 0xe000
	s_nop 0
	global_load_lds_dwordx4 v198, s[68:69]
	s_waitcnt vmcnt(8)
	s_waitcnt lgkmcnt(0)
	s_barrier
	s_setprio 1
	s_waitcnt lgkmcnt(0)
	v_mfma_f32_16x16x32_bf16 v[148:151], v[80:83], v[160:163], v[148:151]
	v_mfma_f32_16x16x32_bf16 v[148:151], v[88:91], v[164:167], v[148:151]
	v_mfma_f32_16x16x32_bf16 v[144:147], v[104:107], v[160:163], v[144:147]
	v_mfma_f32_16x16x32_bf16 v[144:147], v[108:111], v[164:167], v[144:147]
	v_mfma_f32_16x16x32_bf16 v[124:127], v[80:83], v[168:171], v[124:127]
	v_mfma_f32_16x16x32_bf16 v[124:127], v[88:91], v[172:175], v[124:127]
	v_mfma_f32_16x16x32_bf16 v[120:123], v[104:107], v[168:171], v[120:123]
	v_mfma_f32_16x16x32_bf16 v[120:123], v[108:111], v[172:175], v[120:123]
	v_mfma_f32_16x16x32_bf16 v[100:103], v[80:83], v[176:179], v[100:103]
	v_mfma_f32_16x16x32_bf16 v[100:103], v[88:91], v[180:183], v[100:103]
	v_mfma_f32_16x16x32_bf16 v[96:99], v[104:107], v[176:179], v[96:99]
	v_mfma_f32_16x16x32_bf16 v[96:99], v[108:111], v[180:183], v[96:99]
	v_mfma_f32_16x16x32_bf16 v[76:79], v[80:83], v[184:187], v[76:79]
	v_mfma_f32_16x16x32_bf16 v[76:79], v[88:91], v[200:203], v[76:79]
	v_mfma_f32_16x16x32_bf16 v[72:75], v[104:107], v[184:187], v[72:75]
	v_mfma_f32_16x16x32_bf16 v[72:75], v[108:111], v[200:203], v[72:75]
	s_setprio 0
	s_setprio 1
	v_mfma_f32_16x16x32_bf16 v[140:143], v[128:131], v[160:163], v[140:143]
	v_mfma_f32_16x16x32_bf16 v[140:143], v[132:135], v[164:167], v[140:143]
	v_mfma_f32_16x16x32_bf16 v[136:139], v[152:155], v[160:163], v[136:139]
	v_mfma_f32_16x16x32_bf16 v[136:139], v[156:159], v[164:167], v[136:139]
	v_mfma_f32_16x16x32_bf16 v[116:119], v[128:131], v[168:171], v[116:119]
	v_mfma_f32_16x16x32_bf16 v[116:119], v[132:135], v[172:175], v[116:119]
	v_mfma_f32_16x16x32_bf16 v[112:115], v[152:155], v[168:171], v[112:115]
	v_mfma_f32_16x16x32_bf16 v[112:115], v[156:159], v[172:175], v[112:115]
	v_mfma_f32_16x16x32_bf16 v[92:95], v[128:131], v[176:179], v[92:95]
	v_mfma_f32_16x16x32_bf16 v[92:95], v[132:135], v[180:183], v[92:95]
	v_mfma_f32_16x16x32_bf16 v[84:87], v[152:155], v[176:179], v[84:87]
	v_mfma_f32_16x16x32_bf16 v[84:87], v[156:159], v[180:183], v[84:87]
	v_mfma_f32_16x16x32_bf16 v[68:71], v[128:131], v[184:187], v[68:71]
	v_mfma_f32_16x16x32_bf16 v[68:71], v[132:135], v[200:203], v[68:71]
	v_mfma_f32_16x16x32_bf16 v[64:67], v[152:155], v[184:187], v[64:67]
	v_mfma_f32_16x16x32_bf16 v[64:67], v[156:159], v[200:203], v[64:67]
	s_setprio 0
	s_barrier
	s_add_i32 s36, s38, s75
	s_mov_b32 m0, s36
	ds_read_b128 v[160:163], v240 offset:16384
	ds_read_b128 v[164:167], v240 offset:17408
	ds_read_b128 v[168:171], v240 offset:18432
	ds_read_b128 v[172:175], v240 offset:19456
	ds_read_b128 v[176:179], v240 offset:20480
	ds_read_b128 v[180:183], v240 offset:21504
	ds_read_b128 v[184:187], v240 offset:22528
	ds_read_b128 v[200:203], v240 offset:23552
	global_load_lds_dwordx4 v188, s[70:71]
	s_add_i32 m0, s36, 0x2000
	s_add_u32 s36, s70, 0x80000
	s_addc_u32 s37, s71, 0
	s_add_i32 s38, s39, s75
	global_load_lds_dwordx4 v194, s[70:71]
	s_mov_b32 m0, s38
	s_nop 0
	global_load_lds_dwordx4 v188, s[36:37]
	s_add_i32 m0, s38, 0x2000
	s_nop 0
	global_load_lds_dwordx4 v194, s[36:37]
	s_mov_b32 m0, s67
	s_nop 0
	global_load_lds_dwordx4 v188, s[72:73]
	s_mov_b32 m0, s76
	s_nop 0
	global_load_lds_dwordx4 v194, s[72:73]
	s_waitcnt vmcnt(8)
	s_waitcnt lgkmcnt(0)
	s_barrier
	s_setprio 1
	s_waitcnt lgkmcnt(0)
	v_mfma_f32_16x16x32_bf16 v[60:63], v[80:83], v[160:163], v[60:63]
	v_mfma_f32_16x16x32_bf16 v[60:63], v[88:91], v[164:167], v[60:63]
	v_mfma_f32_16x16x32_bf16 v[56:59], v[104:107], v[160:163], v[56:59]
	v_mfma_f32_16x16x32_bf16 v[56:59], v[108:111], v[164:167], v[56:59]
	v_mfma_f32_16x16x32_bf16 v[44:47], v[80:83], v[168:171], v[44:47]
	v_mfma_f32_16x16x32_bf16 v[44:47], v[88:91], v[172:175], v[44:47]
	v_mfma_f32_16x16x32_bf16 v[40:43], v[104:107], v[168:171], v[40:43]
	v_mfma_f32_16x16x32_bf16 v[40:43], v[108:111], v[172:175], v[40:43]
	v_mfma_f32_16x16x32_bf16 v[28:31], v[80:83], v[176:179], v[28:31]
	v_mfma_f32_16x16x32_bf16 v[28:31], v[88:91], v[180:183], v[28:31]
	v_mfma_f32_16x16x32_bf16 v[24:27], v[104:107], v[176:179], v[24:27]
	v_mfma_f32_16x16x32_bf16 v[24:27], v[108:111], v[180:183], v[24:27]
	v_mfma_f32_16x16x32_bf16 v[12:15], v[80:83], v[184:187], v[12:15]
	v_mfma_f32_16x16x32_bf16 v[12:15], v[88:91], v[200:203], v[12:15]
	v_mfma_f32_16x16x32_bf16 v[8:11], v[104:107], v[184:187], v[8:11]
	v_mfma_f32_16x16x32_bf16 v[8:11], v[108:111], v[200:203], v[8:11]
	s_setprio 0
	s_setprio 1
	v_mfma_f32_16x16x32_bf16 v[52:55], v[128:131], v[160:163], v[52:55]
	v_mfma_f32_16x16x32_bf16 v[52:55], v[132:135], v[164:167], v[52:55]
	v_mfma_f32_16x16x32_bf16 v[48:51], v[152:155], v[160:163], v[48:51]
	v_mfma_f32_16x16x32_bf16 v[48:51], v[156:159], v[164:167], v[48:51]
	v_mfma_f32_16x16x32_bf16 v[36:39], v[128:131], v[168:171], v[36:39]
	v_mfma_f32_16x16x32_bf16 v[36:39], v[132:135], v[172:175], v[36:39]
	v_mfma_f32_16x16x32_bf16 v[32:35], v[152:155], v[168:171], v[32:35]
	v_mfma_f32_16x16x32_bf16 v[32:35], v[156:159], v[172:175], v[32:35]
	v_mfma_f32_16x16x32_bf16 v[20:23], v[128:131], v[176:179], v[20:23]
	v_mfma_f32_16x16x32_bf16 v[20:23], v[132:135], v[180:183], v[20:23]
	v_mfma_f32_16x16x32_bf16 v[16:19], v[152:155], v[176:179], v[16:19]
	v_mfma_f32_16x16x32_bf16 v[16:19], v[156:159], v[180:183], v[16:19]
	v_mfma_f32_16x16x32_bf16 v[4:7], v[128:131], v[184:187], v[4:7]
	v_mfma_f32_16x16x32_bf16 v[4:7], v[132:135], v[200:203], v[4:7]
	v_mfma_f32_16x16x32_bf16 v[0:3], v[152:155], v[184:187], v[0:3]
	v_mfma_f32_16x16x32_bf16 v[0:3], v[156:159], v[200:203], v[0:3]
	s_setprio 0
	s_barrier
; #define PG8_STAGE(bufoff, gbase, voff) do { _Pragma("unroll") for (int _i = 0; _i < 2; ++_i) \
;         __builtin_amdgcn_global_load_lds((const unsigned*)((const char*)(gbase) + (voff)[_i]), (PG8_LAS unsigned*)(lds + (bufoff) + ldsw + _i * 8192), 16, 0, 0); } while (0)
; #define PG8_LDA(dst, b, h) do { _Pragma("unroll") for (int m = 0; m < 4; ++m) _Pragma("unroll") for (int k = 0; k < 2; ++k) dst[m][k] = *(const PG8_LAS bf16x8*)(lds + PG8_SA(b, h) + aoff + m * 2048 + k * 1024); } while (0)
; #define PG8_LDB(dst, b, h) do { _Pragma("unroll") for (int n = 0; n < 2; ++n) _Pragma("unroll") for (int k = 0; k < 2; ++k) dst[n][k] = *(const PG8_LAS bf16x8*)(lds + PG8_SB(b, h) + boff + n * 2048 + k * 1024); } while (0)
; #define PG8_MMA(ai, bj, At, Bt) do { __builtin_amdgcn_s_setprio(1); _Pragma("unroll") for (int m = 0; m < 4; ++m) _Pragma("unroll") for (int n = 0; n < 2; ++n) _Pragma("unroll") for (int k = 0; k < 2; ++k) \
;         acc[ai][bj][m][n] = __builtin_amdgcn_mfma_f32_16x16x32_bf16(Bt[n][k], At[m][k], acc[ai][bj][m][n], 0, 0, 0); __builtin_amdgcn_s_setprio(0); } while (0)
; #define PG8_WAIT_V(n) asm volatile("s_waitcnt vmcnt(" #n ")" ::: "memory")
; #define PG8_WAIT_L(n) asm volatile("s_waitcnt lgkmcnt(" #n ")" ::: "memory")
; #define PG8_BAR __builtin_amdgcn_s_barrier()
; #define PG8_SCHED __builtin_amdgcn_sched_barrier(0)
; template <class Epi, class Sched, bool ALIGN_EPI = false, bool SP2 = false>
; __device__ __forceinline__ void gemm_phase(PG8_LAS unsigned char* lds, const Gemm g, const Sched& S, const Epi& E) {
;     ...
;             PG8_LDB(B0, 1, 0); PG8_LDB(B1, 1, 1); PG8_SCHED; PG8_LDA(At, 1, 0); PG8_STAGE(PG8_SA(0, 1), a2 + hstep, voffA);
;             PG8_WAIT_V(8); PG8_WAIT_L(0); PG8_BAR; PG8_MMA(0, 0, At, B0); PG8_MMA(0, 1, At, B1); PG8_BAR; PG8_SCHED;
;             PG8_LDA(At, 1, 1); PG8_STAGE(PG8_SB(1, 0), b3, voffB); PG8_STAGE(PG8_SB(1, 1), b3 + hstep, voffB); PG8_STAGE(PG8_SA(1, 0), a3, voffA);
	s_add_i32 s38, 0, 0x18000
	s_add_i32 s39, 0, 0x1c000
	ds_read_b128 v[80:83], v204 offset:32768
	ds_read_b128 v[88:91], v204 offset:33792
	ds_read_b128 v[104:107], v204 offset:34816
	ds_read_b128 v[108:111], v204 offset:35840
	ds_read_b128 v[128:131], v204 offset:49152
	ds_read_b128 v[132:135], v204 offset:50176
	ds_read_b128 v[152:155], v204 offset:51200
	ds_read_b128 v[156:159], v204 offset:52224
	s_add_u32 s36, s72, 0x80000
	s_addc_u32 s37, s73, 0
	s_mov_b32 m0, s77
	ds_read_b128 v[160:163], v240 offset:32768
	ds_read_b128 v[164:167], v240 offset:33792
	ds_read_b128 v[168:171], v240 offset:34816
	ds_read_b128 v[172:175], v240 offset:35840
	ds_read_b128 v[176:179], v240 offset:36864
	ds_read_b128 v[180:183], v240 offset:37888
	ds_read_b128 v[184:187], v240 offset:38912
	ds_read_b128 v[200:203], v240 offset:39936
	global_load_lds_dwordx4 v188, s[36:37]
	s_mov_b32 m0, s78
	s_nop 0
	global_load_lds_dwordx4 v194, s[36:37]
	s_waitcnt vmcnt(8)
	s_waitcnt lgkmcnt(0)
	s_barrier
	s_setprio 1
	s_waitcnt lgkmcnt(0)
	v_mfma_f32_16x16x32_bf16 v[148:151], v[80:83], v[160:163], v[148:151]
	v_mfma_f32_16x16x32_bf16 v[148:151], v[88:91], v[164:167], v[148:151]
	v_mfma_f32_16x16x32_bf16 v[144:147], v[104:107], v[160:163], v[144:147]
	v_mfma_f32_16x16x32_bf16 v[144:147], v[108:111], v[164:167], v[144:147]
	v_mfma_f32_16x16x32_bf16 v[124:127], v[80:83], v[168:171], v[124:127]
	v_mfma_f32_16x16x32_bf16 v[124:127], v[88:91], v[172:175], v[124:127]
	v_mfma_f32_16x16x32_bf16 v[120:123], v[104:107], v[168:171], v[120:123]
	v_mfma_f32_16x16x32_bf16 v[120:123], v[108:111], v[172:175], v[120:123]
	v_mfma_f32_16x16x32_bf16 v[100:103], v[80:83], v[176:179], v[100:103]
	v_mfma_f32_16x16x32_bf16 v[100:103], v[88:91], v[180:183], v[100:103]
	v_mfma_f32_16x16x32_bf16 v[96:99], v[104:107], v[176:179], v[96:99]
	v_mfma_f32_16x16x32_bf16 v[96:99], v[108:111], v[180:183], v[96:99]
	v_mfma_f32_16x16x32_bf16 v[76:79], v[80:83], v[184:187], v[76:79]
	v_mfma_f32_16x16x32_bf16 v[76:79], v[88:91], v[200:203], v[76:79]
	v_mfma_f32_16x16x32_bf16 v[72:75], v[104:107], v[184:187], v[72:75]
	v_mfma_f32_16x16x32_bf16 v[72:75], v[108:111], v[200:203], v[72:75]
	s_setprio 0
	s_setprio 1
	v_mfma_f32_16x16x32_bf16 v[140:143], v[128:131], v[160:163], v[140:143]
	v_mfma_f32_16x16x32_bf16 v[140:143], v[132:135], v[164:167], v[140:143]
	v_mfma_f32_16x16x32_bf16 v[136:139], v[152:155], v[160:163], v[136:139]
	v_mfma_f32_16x16x32_bf16 v[136:139], v[156:159], v[164:167], v[136:139]
	v_mfma_f32_16x16x32_bf16 v[116:119], v[128:131], v[168:171], v[116:119]
	v_mfma_f32_16x16x32_bf16 v[116:119], v[132:135], v[172:175], v[116:119]
	v_mfma_f32_16x16x32_bf16 v[112:115], v[152:155], v[168:171], v[112:115]
	v_mfma_f32_16x16x32_bf16 v[112:115], v[156:159], v[172:175], v[112:115]
	v_mfma_f32_16x16x32_bf16 v[92:95], v[128:131], v[176:179], v[92:95]
	v_mfma_f32_16x16x32_bf16 v[92:95], v[132:135], v[180:183], v[92:95]
	v_mfma_f32_16x16x32_bf16 v[84:87], v[152:155], v[176:179], v[84:87]
	v_mfma_f32_16x16x32_bf16 v[84:87], v[156:159], v[180:183], v[84:87]
	v_mfma_f32_16x16x32_bf16 v[68:71], v[128:131], v[184:187], v[68:71]
	v_mfma_f32_16x16x32_bf16 v[68:71], v[132:135], v[200:203], v[68:71]
	v_mfma_f32_16x16x32_bf16 v[64:67], v[152:155], v[184:187], v[64:67]
	v_mfma_f32_16x16x32_bf16 v[64:67], v[156:159], v[200:203], v[64:67]
	s_setprio 0
	s_barrier
	s_add_i32 s36, s38, s75
	s_mov_b32 m0, s36
	ds_read_b128 v[160:163], v240 offset:49152
	ds_read_b128 v[164:167], v240 offset:50176
	ds_read_b128 v[168:171], v240 offset:51200
	ds_read_b128 v[172:175], v240 offset:52224
	ds_read_b128 v[176:179], v240 offset:53248
	ds_read_b128 v[180:183], v240 offset:54272
	ds_read_b128 v[184:187], v240 offset:55296
	ds_read_b128 v[200:203], v240 offset:56320
	s_add_u32 s100, s70, 0x80
	s_addc_u32 s101, s71, 0
	global_load_lds_dwordx4 v188, s[100:101]
	s_add_i32 m0, s36, 0x2000
	s_add_u32 s36, s70, 0x80080
	s_addc_u32 s37, s71, 0
	s_add_i32 s38, s39, s75
	global_load_lds_dwordx4 v194, s[100:101]
	s_mov_b32 m0, s38
	s_nop 0
	global_load_lds_dwordx4 v188, s[36:37]
	s_add_i32 m0, s38, 0x2000
	s_nop 0
	global_load_lds_dwordx4 v194, s[36:37]
	s_mov_b32 m0, s79
	s_nop 0
	s_add_u32 s100, s72, 0x80
	s_addc_u32 s101, s73, 0
	global_load_lds_dwordx4 v188, s[100:101]
	s_mov_b32 m0, s80
	s_nop 0
	global_load_lds_dwordx4 v194, s[100:101]
	s_waitcnt vmcnt(8)
	s_waitcnt lgkmcnt(0)
	s_barrier
; __device__ __forceinline__ unsigned cvt_pk_bf16(float lo, float hi) { unsigned r; asm volatile("v_cvt_pk_bf16_f32 %0, %1, %2" : "=v"(r) : "v"(lo), "v"(hi)); return r; }
; #define PG8_WAIT_V(n) asm volatile("s_waitcnt vmcnt(" #n ")" ::: "memory")
; #define PG8_WAIT_L(n) asm volatile("s_waitcnt lgkmcnt(" #n ")" ::: "memory")
; #define PG8_BAR __builtin_amdgcn_s_barrier()
; #define PG8_SCHED __builtin_amdgcn_sched_barrier(0)
;     __device__ __forceinline__ void operator()(const f32x4 (&acc)[2][2][4][2], const Unit& u, int wr, int wc, int fr, int fq) const {
;         const int r0 = u.pm * BM + wr * 64 + fr, c0 = u.pn * BM + 32 * wc + 8 * fq;
;         u32x4 hold[2][4][2];
; #pragma unroll
;         for (int ai = 0; ai < 2; ++ai)
; #pragma unroll
;             for (int m = 0; m < 4; ++m)
; #pragma unroll
;                 for (int bj = 0; bj < 2; ++bj) hold[ai][m][bj] = *(const u32x4*)(HB + (size_t)(r0 + ai * HALF + m * 16) * 2048 + c0 + bj * HALF);
; #pragma unroll
;         for (int ai = 0; ai < 2; ++ai)
; #pragma unroll
;             for (int m = 0; m < 4; ++m) {
;                 const int r = r0 + ai * HALF + m * 16;
;                 const bool valid = r < NREAL + NMETA;
;                 float ssum = 0.f;
; #pragma unroll
;                 for (int bj = 0; bj < 2; ++bj) {
;                     const u32x4 hv = hold[ai][m][bj];
;                     f32x4 h0 = {__uint_as_float(hv.x << 16), __uint_as_float(hv.x & 0xffff0000u), __uint_as_float(hv.y << 16), __uint_as_float(hv.y & 0xffff0000u)};
;                     f32x4 h1 = {__uint_as_float(hv.z << 16), __uint_as_float(hv.z & 0xffff0000u), __uint_as_float(hv.w << 16), __uint_as_float(hv.w & 0xffff0000u)};
;                     h0 += acc[ai][bj][m][0]; h1 += acc[ai][bj][m][1];
;                     const int col0 = c0 + bj * HALF;
;                     u32x4 w; w.x = cvt_pk_bf16(h0[0], h0[1]); w.y = cvt_pk_bf16(h0[2], h0[3]); w.z = cvt_pk_bf16(h1[0], h1[1]); w.w = cvt_pk_bf16(h1[2], h1[3]);
;                     if (valid) *(u32x4*)(HB + (size_t)r * 2048 + col0) = w;
; template <class Epi, class Sched, bool ALIGN_EPI = false, bool SP2 = false>
; __device__ __forceinline__ void gemm_phase(PG8_LAS unsigned char* lds, const Gemm g, const Sched& S, const Epi& E) {
;     ...
;             PG8_WAIT_V(8); PG8_WAIT_L(0); PG8_BAR; PG8_MMA(1, 0, At, B0); PG8_MMA(1, 1, At, B1); PG8_BAR; PG8_SCHED;
	s_setprio 1
	s_waitcnt lgkmcnt(0)
	v_mfma_f32_16x16x32_bf16 v[60:63], v[80:83], v[160:163], v[60:63]
	v_mfma_f32_16x16x32_bf16 v[60:63], v[88:91], v[164:167], v[60:63]
	v_mfma_f32_16x16x32_bf16 v[56:59], v[104:107], v[160:163], v[56:59]
	v_mfma_f32_16x16x32_bf16 v[56:59], v[108:111], v[164:167], v[56:59]
	v_mfma_f32_16x16x32_bf16 v[44:47], v[80:83], v[168:171], v[44:47]
	v_mfma_f32_16x16x32_bf16 v[44:47], v[88:91], v[172:175], v[44:47]
	v_mfma_f32_16x16x32_bf16 v[40:43], v[104:107], v[168:171], v[40:43]
	v_mfma_f32_16x16x32_bf16 v[40:43], v[108:111], v[172:175], v[40:43]
	v_mfma_f32_16x16x32_bf16 v[28:31], v[80:83], v[176:179], v[28:31]
	v_mfma_f32_16x16x32_bf16 v[28:31], v[88:91], v[180:183], v[28:31]
	v_mfma_f32_16x16x32_bf16 v[24:27], v[104:107], v[176:179], v[24:27]
	v_mfma_f32_16x16x32_bf16 v[24:27], v[108:111], v[180:183], v[24:27]
	v_mfma_f32_16x16x32_bf16 v[12:15], v[80:83], v[184:187], v[12:15]
	v_mfma_f32_16x16x32_bf16 v[12:15], v[88:91], v[200:203], v[12:15]
	v_mfma_f32_16x16x32_bf16 v[8:11], v[104:107], v[184:187], v[8:11]
	v_mfma_f32_16x16x32_bf16 v[8:11], v[108:111], v[200:203], v[8:11]
	s_setprio 0
	s_setprio 1
	v_mfma_f32_16x16x32_bf16 v[52:55], v[128:131], v[160:163], v[52:55]
	v_mfma_f32_16x16x32_bf16 v[52:55], v[132:135], v[164:167], v[52:55]
	v_mfma_f32_16x16x32_bf16 v[48:51], v[152:155], v[160:163], v[48:51]
	v_mfma_f32_16x16x32_bf16 v[48:51], v[156:159], v[164:167], v[48:51]
	v_mfma_f32_16x16x32_bf16 v[36:39], v[128:131], v[168:171], v[36:39]
	v_mfma_f32_16x16x32_bf16 v[36:39], v[132:135], v[172:175], v[36:39]
	v_mfma_f32_16x16x32_bf16 v[32:35], v[152:155], v[168:171], v[32:35]
	v_mfma_f32_16x16x32_bf16 v[32:35], v[156:159], v[172:175], v[32:35]
	v_mfma_f32_16x16x32_bf16 v[20:23], v[128:131], v[176:179], v[20:23]
	v_mfma_f32_16x16x32_bf16 v[20:23], v[132:135], v[180:183], v[20:23]
	v_mfma_f32_16x16x32_bf16 v[16:19], v[152:155], v[176:179], v[16:19]
	v_mfma_f32_16x16x32_bf16 v[16:19], v[156:159], v[180:183], v[16:19]
	v_mfma_f32_16x16x32_bf16 v[4:7], v[128:131], v[184:187], v[4:7]
	v_mfma_f32_16x16x32_bf16 v[4:7], v[132:135], v[200:203], v[4:7]
	v_mfma_f32_16x16x32_bf16 v[0:3], v[152:155], v[184:187], v[0:3]
	v_mfma_f32_16x16x32_bf16 v[0:3], v[156:159], v[200:203], v[0:3]
	s_setprio 0
	s_barrier
	s_add_i32 s89, s89, 2
	s_add_u32 s68, s68, 0x100
	s_addc_u32 s69, s69, 0
	s_add_u32 s3, s3, 0x100
	s_addc_u32 s88, s88, 0
	s_cmp_gt_u32 s89, 29
	s_cbranch_scc0 .LBB0_205
	v_lshl_add_u32 v202, s66, 8, v237
	v_lshl_or_b32 v200, s8, 8, v239
	v_ashrrev_i32_e32 v201, 31, v200
	v_ashrrev_i32_e32 v203, 31, v202
	v_or_b32_e32 v222, 16, v202
	v_lshl_add_u64 v[80:81], v[200:201], 1, s[34:35]
	v_lshlrev_b64 v[242:243], 12, v[202:203]
	v_ashrrev_i32_e32 v223, 31, v222
	v_or_b32_e32 v218, 32, v202
	v_lshl_add_u64 v[82:83], v[80:81], 0, v[242:243]
	v_lshlrev_b64 v[220:221], 12, v[222:223]
	v_ashrrev_i32_e32 v219, 31, v218
	v_or_b32_e32 v214, 48, v202
	global_load_dwordx4 v[228:231], v[82:83], off
	global_load_dwordx4 v[184:187], v[82:83], off offset:256
	v_lshl_add_u64 v[82:83], v[80:81], 0, v[220:221]
	v_lshlrev_b64 v[216:217], 12, v[218:219]
	v_ashrrev_i32_e32 v215, 31, v214
	s_mov_b64 s[8:9], 0x80000
	global_load_dwordx4 v[180:183], v[82:83], off
	global_load_dwordx4 v[176:179], v[82:83], off offset:256
	v_lshl_add_u64 v[82:83], v[80:81], 0, v[216:217]
	v_lshlrev_b64 v[212:213], 12, v[214:215]
	v_lshl_add_u64 v[210:211], v[242:243], 0, s[8:9]
	s_mov_b64 s[8:9], 0x90000
	global_load_dwordx4 v[172:175], v[82:83], off
	global_load_dwordx4 v[168:171], v[82:83], off offset:256
	v_lshl_add_u64 v[82:83], v[80:81], 0, v[212:213]
	v_lshl_add_u64 v[208:209], v[242:243], 0, s[8:9]
	s_mov_b64 s[8:9], 0xa0000
	global_load_dwordx4 v[164:167], v[82:83], off
	global_load_dwordx4 v[160:163], v[82:83], off offset:256
	v_lshl_add_u64 v[82:83], v[80:81], 0, v[210:211]
	v_lshl_add_u64 v[206:207], v[242:243], 0, s[8:9]
	s_mov_b64 s[8:9], 0xb0000
	global_load_dwordx4 v[156:159], v[82:83], off
	global_load_dwordx4 v[152:155], v[82:83], off offset:256
	v_lshl_add_u64 v[82:83], v[80:81], 0, v[208:209]
	v_lshl_add_u64 v[204:205], v[242:243], 0, s[8:9]
	global_load_dwordx4 v[132:135], v[82:83], off
	global_load_dwordx4 v[128:131], v[82:83], off offset:256
	v_lshl_add_u64 v[82:83], v[80:81], 0, v[206:207]
	v_lshl_add_u64 v[80:81], v[80:81], 0, v[204:205]
	global_load_dwordx4 v[108:111], v[82:83], off
	global_load_dwordx4 v[104:107], v[82:83], off offset:256
	global_load_dwordx4 v[88:91], v[80:81], off
	s_nop 0
	global_load_dwordx4 v[80:83], v[80:81], off offset:256
	v_lshl_add_u64 v[242:243], s[34:35], 0, v[242:243]
	s_and_b64 vcc, exec, s[56:57]
	s_cbranch_vccz .LBB0_208
	s_barrier
.LBB0_208:
	v_cmp_gt_i32_e32 vcc, s84, v202
	s_waitcnt vmcnt(0)
	v_lshlrev_b32_e32 v244, 16, v228
	v_and_b32_e32 v245, 0xffff0000, v228
	v_lshlrev_b32_e32 v228, 16, v229
	v_and_b32_e32 v229, 0xffff0000, v229
	v_lshlrev_b32_e32 v246, 16, v230
	v_and_b32_e32 v247, 0xffff0000, v230
	v_lshlrev_b32_e32 v230, 16, v231
	v_and_b32_e32 v231, 0xffff0000, v231
	v_pk_add_f32 v[148:149], v[148:149], v[244:245]
	v_pk_add_f32 v[150:151], v[150:151], v[228:229]
	v_pk_add_f32 v[228:229], v[146:147], v[230:231]
	v_pk_add_f32 v[146:147], v[144:145], v[246:247]
	v_cvt_pk_bf16_f32 v144, v148, v149
	v_lshl_add_u64 v[148:149], v[200:201], 1, v[242:243]
	v_cvt_pk_bf16_f32 v145, v150, v151
	v_cvt_pk_bf16_f32 v146, v146, v147
	v_cvt_pk_bf16_f32 v147, v228, v229
	s_and_saveexec_b64 s[8:9], vcc
	s_cbranch_execz .LBB0_210
	global_store_dwordx4 v[148:149], v[144:147], off

; #define PG8_STAGE(bufoff, gbase, voff) do { _Pragma("unroll") for (int _i = 0; _i < 2; ++_i) \
;         __builtin_amdgcn_global_load_lds((const unsigned*)((const char*)(gbase) + (voff)[_i]), (PG8_LAS unsigned*)(lds + (bufoff) + ldsw + _i * 8192), 16, 0, 0); } while (0)
; #define PG8_LDA(dst, b, h) do { _Pragma("unroll") for (int m = 0; m < 4; ++m) _Pragma("unroll") for (int k = 0; k < 2; ++k) dst[m][k] = *(const PG8_LAS bf16x8*)(lds + PG8_SA(b, h) + aoff + m * 2048 + k * 1024); } while (0)
; #define PG8_LDB(dst, b, h) do { _Pragma("unroll") for (int n = 0; n < 2; ++n) _Pragma("unroll") for (int k = 0; k < 2; ++k) dst[n][k] = *(const PG8_LAS bf16x8*)(lds + PG8_SB(b, h) + boff + n * 2048 + k * 1024); } while (0)
; #define PG8_MMA(ai, bj, At, Bt) do { __builtin_amdgcn_s_setprio(1); _Pragma("unroll") for (int m = 0; m < 4; ++m) _Pragma("unroll") for (int n = 0; n < 2; ++n) _Pragma("unroll") for (int k = 0; k < 2; ++k) \
;         acc[ai][bj][m][n] = __builtin_amdgcn_mfma_f32_16x16x32_bf16(Bt[n][k], At[m][k], acc[ai][bj][m][n], 0, 0, 0); __builtin_amdgcn_s_setprio(0); } while (0)
; #define PG8_WAIT_V(n) asm volatile("s_waitcnt vmcnt(" #n ")" ::: "memory")
; #define PG8_WAIT_L(n) asm volatile("s_waitcnt lgkmcnt(" #n ")" ::: "memory")
; #define PG8_BAR __builtin_amdgcn_s_barrier()
; #define PG8_SCHED __builtin_amdgcn_sched_barrier(0)
; template <class Epi, class Sched, bool ALIGN_EPI = false, bool SP2 = false>
; __device__ __forceinline__ void gemm_phase(PG8_LAS unsigned char* lds, const Gemm g, const Sched& S, const Epi& E) {
;     ...
;             PG8_LDB(B0, 0, 0); PG8_LDB(B1, 0, 1); PG8_SCHED; PG8_LDA(At, 0, 0); PG8_STAGE(PG8_SA(1, 1), a1 + hstep, voffA);
;             PG8_WAIT_V(8); PG8_WAIT_L(0); PG8_BAR; PG8_MMA(0, 0, At, B0); PG8_MMA(0, 1, At, B1); PG8_BAR; PG8_SCHED;
;             PG8_LDA(At, 0, 1); PG8_STAGE(PG8_SB(0, 0), b2, voffB); PG8_STAGE(PG8_SB(0, 1), b2 + hstep, voffB); PG8_STAGE(PG8_SA(0, 0), a2, voffA);
;             PG8_WAIT_V(8); PG8_WAIT_L(0); PG8_BAR; PG8_MMA(1, 0, At, B0); PG8_MMA(1, 1, At, B1); PG8_BAR; PG8_SCHED;
.LBB0_298:
	s_add_u32 s36, vcc_lo, 0xfff80080
	s_addc_u32 s37, vcc_hi, -1
	s_add_i32 s38, 0, 0x10000
	s_cmp_eq_u32 s95, 28
	s_cselect_b32 s71, s65, s37
	s_cselect_b32 s70, s67, s36
	s_cselect_b32 s69, s73, s94
	s_cselect_b32 s68, s75, s3
	s_add_i32 s39, 0, 0x14000
	ds_read_b128 v[64:67], v214
	ds_read_b128 v[68:71], v214 offset:1024
	ds_read_b128 v[72:75], v214 offset:2048
	ds_read_b128 v[146:149], v214 offset:3072
	ds_read_b128 v[150:153], v214 offset:16384
	ds_read_b128 v[154:157], v214 offset:17408
	ds_read_b128 v[158:161], v214 offset:18432
	ds_read_b128 v[170:173], v214 offset:19456
	s_add_i32 m0, s88, 0xc000
	ds_read_b128 v[174:177], v169
	ds_read_b128 v[178:181], v169 offset:1024
	ds_read_b128 v[182:185], v169 offset:2048
	ds_read_b128 v[194:197], v169 offset:3072
	ds_read_b128 v[198:201], v169 offset:4096
	ds_read_b128 v[202:205], v169 offset:5120
	ds_read_b128 v[206:209], v169 offset:6144
	ds_read_b128 v[210:213], v169 offset:7168
	global_load_lds_dwordx4 v142, vcc
	s_add_i32 m0, s88, 0xe000
	s_nop 0
	global_load_lds_dwordx4 v144, vcc
	s_waitcnt vmcnt(8)
	s_waitcnt lgkmcnt(0)
	s_barrier
	s_setprio 1
	s_waitcnt lgkmcnt(0)
	v_mfma_f32_16x16x32_bf16 v[136:139], v[64:67], v[174:177], v[136:139]
	v_mfma_f32_16x16x32_bf16 v[136:139], v[68:71], v[178:181], v[136:139]
	v_mfma_f32_16x16x32_bf16 v[132:135], v[72:75], v[174:177], v[132:135]
	v_mfma_f32_16x16x32_bf16 v[132:135], v[146:149], v[178:181], v[132:135]
	v_mfma_f32_16x16x32_bf16 v[120:123], v[64:67], v[182:185], v[120:123]
	v_mfma_f32_16x16x32_bf16 v[120:123], v[68:71], v[194:197], v[120:123]
	v_mfma_f32_16x16x32_bf16 v[116:119], v[72:75], v[182:185], v[116:119]
	v_mfma_f32_16x16x32_bf16 v[116:119], v[146:149], v[194:197], v[116:119]
	v_mfma_f32_16x16x32_bf16 v[104:107], v[64:67], v[198:201], v[104:107]
	v_mfma_f32_16x16x32_bf16 v[104:107], v[68:71], v[202:205], v[104:107]
	v_mfma_f32_16x16x32_bf16 v[100:103], v[72:75], v[198:201], v[100:103]
	v_mfma_f32_16x16x32_bf16 v[100:103], v[146:149], v[202:205], v[100:103]
	v_mfma_f32_16x16x32_bf16 v[88:91], v[64:67], v[206:209], v[88:91]
	v_mfma_f32_16x16x32_bf16 v[88:91], v[68:71], v[210:213], v[88:91]
	v_mfma_f32_16x16x32_bf16 v[84:87], v[72:75], v[206:209], v[84:87]
	v_mfma_f32_16x16x32_bf16 v[84:87], v[146:149], v[210:213], v[84:87]
	s_setprio 0
	s_setprio 1
	v_mfma_f32_16x16x32_bf16 v[128:131], v[150:153], v[174:177], v[128:131]
	v_mfma_f32_16x16x32_bf16 v[128:131], v[154:157], v[178:181], v[128:131]
	v_mfma_f32_16x16x32_bf16 v[124:127], v[158:161], v[174:177], v[124:127]
	v_mfma_f32_16x16x32_bf16 v[124:127], v[170:173], v[178:181], v[124:127]
	v_mfma_f32_16x16x32_bf16 v[112:115], v[150:153], v[182:185], v[112:115]
	v_mfma_f32_16x16x32_bf16 v[112:115], v[154:157], v[194:197], v[112:115]
	v_mfma_f32_16x16x32_bf16 v[108:111], v[158:161], v[182:185], v[108:111]
	v_mfma_f32_16x16x32_bf16 v[108:111], v[170:173], v[194:197], v[108:111]
	v_mfma_f32_16x16x32_bf16 v[96:99], v[150:153], v[198:201], v[96:99]
	v_mfma_f32_16x16x32_bf16 v[96:99], v[154:157], v[202:205], v[96:99]
	v_mfma_f32_16x16x32_bf16 v[92:95], v[158:161], v[198:201], v[92:95]
	v_mfma_f32_16x16x32_bf16 v[92:95], v[170:173], v[202:205], v[92:95]
	v_mfma_f32_16x16x32_bf16 v[80:83], v[150:153], v[206:209], v[80:83]
	v_mfma_f32_16x16x32_bf16 v[80:83], v[154:157], v[210:213], v[80:83]
	v_mfma_f32_16x16x32_bf16 v[76:79], v[158:161], v[206:209], v[76:79]
	v_mfma_f32_16x16x32_bf16 v[76:79], v[170:173], v[210:213], v[76:79]
	s_setprio 0
	s_barrier
	s_add_i32 s36, s38, s87
	s_mov_b32 m0, s36
	ds_read_b128 v[174:177], v169 offset:16384
	ds_read_b128 v[178:181], v169 offset:17408
	ds_read_b128 v[182:185], v169 offset:18432
	ds_read_b128 v[194:197], v169 offset:19456
	ds_read_b128 v[198:201], v169 offset:20480
	ds_read_b128 v[202:205], v169 offset:21504
	ds_read_b128 v[206:209], v169 offset:22528
	ds_read_b128 v[210:213], v169 offset:23552
	global_load_lds_dwordx4 v188, s[68:69]
	s_add_i32 m0, s36, 0x2000
	s_add_u32 s36, s68, 0x80000
	s_addc_u32 s37, s69, 0
	s_add_i32 s38, s39, s87
	global_load_lds_dwordx4 v140, s[68:69]
	s_mov_b32 m0, s38
	s_nop 0
	global_load_lds_dwordx4 v188, s[36:37]
	s_add_i32 m0, s38, 0x2000
	s_nop 0
	global_load_lds_dwordx4 v140, s[36:37]
	s_mov_b32 m0, s88
	s_nop 0
	global_load_lds_dwordx4 v188, s[70:71]
	s_mov_b32 m0, s89
	s_nop 0
	global_load_lds_dwordx4 v140, s[70:71]
	s_waitcnt vmcnt(8)
	s_waitcnt lgkmcnt(0)
	s_barrier
	s_setprio 1
	s_waitcnt lgkmcnt(0)
	v_mfma_f32_16x16x32_bf16 v[56:59], v[64:67], v[174:177], v[56:59]
	v_mfma_f32_16x16x32_bf16 v[56:59], v[68:71], v[178:181], v[56:59]
	v_mfma_f32_16x16x32_bf16 v[60:63], v[72:75], v[174:177], v[60:63]
	v_mfma_f32_16x16x32_bf16 v[60:63], v[146:149], v[178:181], v[60:63]
	v_mfma_f32_16x16x32_bf16 v[40:43], v[64:67], v[182:185], v[40:43]
	v_mfma_f32_16x16x32_bf16 v[40:43], v[68:71], v[194:197], v[40:43]
	v_mfma_f32_16x16x32_bf16 v[44:47], v[72:75], v[182:185], v[44:47]
	v_mfma_f32_16x16x32_bf16 v[44:47], v[146:149], v[194:197], v[44:47]
	v_mfma_f32_16x16x32_bf16 v[24:27], v[64:67], v[198:201], v[24:27]
	v_mfma_f32_16x16x32_bf16 v[24:27], v[68:71], v[202:205], v[24:27]
	v_mfma_f32_16x16x32_bf16 v[28:31], v[72:75], v[198:201], v[28:31]
	v_mfma_f32_16x16x32_bf16 v[28:31], v[146:149], v[202:205], v[28:31]
	v_mfma_f32_16x16x32_bf16 v[8:11], v[64:67], v[206:209], v[8:11]
	v_mfma_f32_16x16x32_bf16 v[8:11], v[68:71], v[210:213], v[8:11]
	v_mfma_f32_16x16x32_bf16 v[12:15], v[72:75], v[206:209], v[12:15]
	v_mfma_f32_16x16x32_bf16 v[12:15], v[146:149], v[210:213], v[12:15]
	s_setprio 0
	s_setprio 1
	v_mfma_f32_16x16x32_bf16 v[52:55], v[150:153], v[174:177], v[52:55]
	v_mfma_f32_16x16x32_bf16 v[52:55], v[154:157], v[178:181], v[52:55]
	v_mfma_f32_16x16x32_bf16 v[48:51], v[158:161], v[174:177], v[48:51]
	v_mfma_f32_16x16x32_bf16 v[48:51], v[170:173], v[178:181], v[48:51]
	v_mfma_f32_16x16x32_bf16 v[36:39], v[150:153], v[182:185], v[36:39]
	v_mfma_f32_16x16x32_bf16 v[36:39], v[154:157], v[194:197], v[36:39]
	v_mfma_f32_16x16x32_bf16 v[32:35], v[158:161], v[182:185], v[32:35]
	v_mfma_f32_16x16x32_bf16 v[32:35], v[170:173], v[194:197], v[32:35]
	v_mfma_f32_16x16x32_bf16 v[20:23], v[150:153], v[198:201], v[20:23]
	v_mfma_f32_16x16x32_bf16 v[20:23], v[154:157], v[202:205], v[20:23]
	v_mfma_f32_16x16x32_bf16 v[16:19], v[158:161], v[198:201], v[16:19]
	v_mfma_f32_16x16x32_bf16 v[16:19], v[170:173], v[202:205], v[16:19]
	v_mfma_f32_16x16x32_bf16 v[4:7], v[150:153], v[206:209], v[4:7]
	v_mfma_f32_16x16x32_bf16 v[4:7], v[154:157], v[210:213], v[4:7]
	v_mfma_f32_16x16x32_bf16 v[0:3], v[158:161], v[206:209], v[0:3]
	v_mfma_f32_16x16x32_bf16 v[0:3], v[170:173], v[210:213], v[0:3]
	s_setprio 0
	s_barrier
; #define PG8_STAGE(bufoff, gbase, voff) do { _Pragma("unroll") for (int _i = 0; _i < 2; ++_i) \
;         __builtin_amdgcn_global_load_lds((const unsigned*)((const char*)(gbase) + (voff)[_i]), (PG8_LAS unsigned*)(lds + (bufoff) + ldsw + _i * 8192), 16, 0, 0); } while (0)
; #define PG8_LDA(dst, b, h) do { _Pragma("unroll") for (int m = 0; m < 4; ++m) _Pragma("unroll") for (int k = 0; k < 2; ++k) dst[m][k] = *(const PG8_LAS bf16x8*)(lds + PG8_SA(b, h) + aoff + m * 2048 + k * 1024); } while (0)
; #define PG8_LDB(dst, b, h) do { _Pragma("unroll") for (int n = 0; n < 2; ++n) _Pragma("unroll") for (int k = 0; k < 2; ++k) dst[n][k] = *(const PG8_LAS bf16x8*)(lds + PG8_SB(b, h) + boff + n * 2048 + k * 1024); } while (0)
; #define PG8_MMA(ai, bj, At, Bt) do { __builtin_amdgcn_s_setprio(1); _Pragma("unroll") for (int m = 0; m < 4; ++m) _Pragma("unroll") for (int n = 0; n < 2; ++n) _Pragma("unroll") for (int k = 0; k < 2; ++k) \
;         acc[ai][bj][m][n] = __builtin_amdgcn_mfma_f32_16x16x32_bf16(Bt[n][k], At[m][k], acc[ai][bj][m][n], 0, 0, 0); __builtin_amdgcn_s_setprio(0); } while (0)
; #define PG8_WAIT_V(n) asm volatile("s_waitcnt vmcnt(" #n ")" ::: "memory")
; #define PG8_WAIT_L(n) asm volatile("s_waitcnt lgkmcnt(" #n ")" ::: "memory")
; #define PG8_BAR __builtin_amdgcn_s_barrier()
; #define PG8_SCHED __builtin_amdgcn_sched_barrier(0)
; template <class Epi, class Sched, bool ALIGN_EPI = false, bool SP2 = false>
; __device__ __forceinline__ void gemm_phase(PG8_LAS unsigned char* lds, const Gemm g, const Sched& S, const Epi& E) {
;     ...
;             PG8_LDB(B0, 1, 0); PG8_LDB(B1, 1, 1); PG8_SCHED; PG8_LDA(At, 1, 0); PG8_STAGE(PG8_SA(0, 1), a2 + hstep, voffA);
;             PG8_WAIT_V(8); PG8_WAIT_L(0); PG8_BAR; PG8_MMA(0, 0, At, B0); PG8_MMA(0, 1, At, B1); PG8_BAR; PG8_SCHED;
;             PG8_LDA(At, 1, 1); PG8_STAGE(PG8_SB(1, 0), b3, voffB); PG8_STAGE(PG8_SB(1, 1), b3 + hstep, voffB); PG8_STAGE(PG8_SA(1, 0), a3, voffA);
;             PG8_WAIT_V(8); PG8_WAIT_L(0); PG8_BAR; PG8_MMA(1, 0, At, B0); PG8_MMA(1, 1, At, B1); PG8_BAR; PG8_SCHED;
	s_add_i32 s38, 0, 0x18000
	s_add_i32 s39, 0, 0x1c000
	ds_read_b128 v[64:67], v214 offset:32768
	ds_read_b128 v[68:71], v214 offset:33792
	ds_read_b128 v[72:75], v214 offset:34816
	ds_read_b128 v[146:149], v214 offset:35840
	ds_read_b128 v[150:153], v214 offset:49152
	ds_read_b128 v[154:157], v214 offset:50176
	ds_read_b128 v[158:161], v214 offset:51200
	ds_read_b128 v[170:173], v214 offset:52224
	s_add_u32 s36, s70, 0x80000
	s_addc_u32 s37, s71, 0
	s_mov_b32 m0, s14
	ds_read_b128 v[174:177], v169 offset:32768
	ds_read_b128 v[178:181], v169 offset:33792
	ds_read_b128 v[182:185], v169 offset:34816
	ds_read_b128 v[194:197], v169 offset:35840
	ds_read_b128 v[198:201], v169 offset:36864
	ds_read_b128 v[202:205], v169 offset:37888
	ds_read_b128 v[206:209], v169 offset:38912
	ds_read_b128 v[210:213], v169 offset:39936
	global_load_lds_dwordx4 v188, s[36:37]
	s_mov_b32 m0, s15
	s_nop 0
	global_load_lds_dwordx4 v140, s[36:37]
	s_waitcnt vmcnt(8)
	s_waitcnt lgkmcnt(0)
	s_barrier
	s_setprio 1
	s_waitcnt lgkmcnt(0)
	v_mfma_f32_16x16x32_bf16 v[136:139], v[64:67], v[174:177], v[136:139]
	v_mfma_f32_16x16x32_bf16 v[136:139], v[68:71], v[178:181], v[136:139]
	v_mfma_f32_16x16x32_bf16 v[132:135], v[72:75], v[174:177], v[132:135]
	v_mfma_f32_16x16x32_bf16 v[132:135], v[146:149], v[178:181], v[132:135]
	v_mfma_f32_16x16x32_bf16 v[120:123], v[64:67], v[182:185], v[120:123]
	v_mfma_f32_16x16x32_bf16 v[120:123], v[68:71], v[194:197], v[120:123]
	v_mfma_f32_16x16x32_bf16 v[116:119], v[72:75], v[182:185], v[116:119]
	v_mfma_f32_16x16x32_bf16 v[116:119], v[146:149], v[194:197], v[116:119]
	v_mfma_f32_16x16x32_bf16 v[104:107], v[64:67], v[198:201], v[104:107]
	v_mfma_f32_16x16x32_bf16 v[104:107], v[68:71], v[202:205], v[104:107]
	v_mfma_f32_16x16x32_bf16 v[100:103], v[72:75], v[198:201], v[100:103]
	v_mfma_f32_16x16x32_bf16 v[100:103], v[146:149], v[202:205], v[100:103]
	v_mfma_f32_16x16x32_bf16 v[88:91], v[64:67], v[206:209], v[88:91]
	v_mfma_f32_16x16x32_bf16 v[88:91], v[68:71], v[210:213], v[88:91]
	v_mfma_f32_16x16x32_bf16 v[84:87], v[72:75], v[206:209], v[84:87]
	v_mfma_f32_16x16x32_bf16 v[84:87], v[146:149], v[210:213], v[84:87]
	s_setprio 0
	s_setprio 1
	v_mfma_f32_16x16x32_bf16 v[128:131], v[150:153], v[174:177], v[128:131]
	v_mfma_f32_16x16x32_bf16 v[128:131], v[154:157], v[178:181], v[128:131]
	v_mfma_f32_16x16x32_bf16 v[124:127], v[158:161], v[174:177], v[124:127]
	v_mfma_f32_16x16x32_bf16 v[124:127], v[170:173], v[178:181], v[124:127]
	v_mfma_f32_16x16x32_bf16 v[112:115], v[150:153], v[182:185], v[112:115]
	v_mfma_f32_16x16x32_bf16 v[112:115], v[154:157], v[194:197], v[112:115]
	v_mfma_f32_16x16x32_bf16 v[108:111], v[158:161], v[182:185], v[108:111]
	v_mfma_f32_16x16x32_bf16 v[108:111], v[170:173], v[194:197], v[108:111]
	v_mfma_f32_16x16x32_bf16 v[96:99], v[150:153], v[198:201], v[96:99]
	v_mfma_f32_16x16x32_bf16 v[96:99], v[154:157], v[202:205], v[96:99]
	v_mfma_f32_16x16x32_bf16 v[92:95], v[158:161], v[198:201], v[92:95]
	v_mfma_f32_16x16x32_bf16 v[92:95], v[170:173], v[202:205], v[92:95]
	v_mfma_f32_16x16x32_bf16 v[80:83], v[150:153], v[206:209], v[80:83]
	v_mfma_f32_16x16x32_bf16 v[80:83], v[154:157], v[210:213], v[80:83]
	v_mfma_f32_16x16x32_bf16 v[76:79], v[158:161], v[206:209], v[76:79]
	v_mfma_f32_16x16x32_bf16 v[76:79], v[170:173], v[210:213], v[76:79]
	s_setprio 0
	s_barrier
	s_add_i32 s36, s38, s87
	s_mov_b32 m0, s36
	ds_read_b128 v[174:177], v169 offset:49152
	ds_read_b128 v[178:181], v169 offset:50176
	ds_read_b128 v[182:185], v169 offset:51200
	ds_read_b128 v[194:197], v169 offset:52224
	ds_read_b128 v[198:201], v169 offset:53248
	ds_read_b128 v[202:205], v169 offset:54272
	ds_read_b128 v[206:209], v169 offset:55296
	ds_read_b128 v[210:213], v169 offset:56320
	s_add_u32 s100, s68, 0x80
	s_addc_u32 s101, s69, 0
	global_load_lds_dwordx4 v188, s[100:101]
	s_add_i32 m0, s36, 0x2000
	s_add_u32 s36, s68, 0x80080
	s_addc_u32 s37, s69, 0
	s_add_i32 s38, s39, s87
	global_load_lds_dwordx4 v140, s[100:101]
	s_mov_b32 m0, s38
	s_nop 0
	global_load_lds_dwordx4 v188, s[36:37]
	s_add_i32 m0, s38, 0x2000
	s_nop 0
	global_load_lds_dwordx4 v140, s[36:37]
	s_mov_b32 m0, s81
	s_nop 0
	s_add_u32 s100, s70, 0x80
	s_addc_u32 s101, s71, 0
	global_load_lds_dwordx4 v188, s[100:101]
	s_mov_b32 m0, s80
	s_nop 0
	global_load_lds_dwordx4 v140, s[100:101]
	s_waitcnt vmcnt(8)
	s_waitcnt lgkmcnt(0)
	s_barrier
	s_setprio 1
	s_waitcnt lgkmcnt(0)
	v_mfma_f32_16x16x32_bf16 v[56:59], v[64:67], v[174:177], v[56:59]
	v_mfma_f32_16x16x32_bf16 v[56:59], v[68:71], v[178:181], v[56:59]
	v_mfma_f32_16x16x32_bf16 v[60:63], v[72:75], v[174:177], v[60:63]
	v_mfma_f32_16x16x32_bf16 v[60:63], v[146:149], v[178:181], v[60:63]
	v_mfma_f32_16x16x32_bf16 v[40:43], v[64:67], v[182:185], v[40:43]
	v_mfma_f32_16x16x32_bf16 v[40:43], v[68:71], v[194:197], v[40:43]
	v_mfma_f32_16x16x32_bf16 v[44:47], v[72:75], v[182:185], v[44:47]
	v_mfma_f32_16x16x32_bf16 v[44:47], v[146:149], v[194:197], v[44:47]
	v_mfma_f32_16x16x32_bf16 v[24:27], v[64:67], v[198:201], v[24:27]
	v_mfma_f32_16x16x32_bf16 v[24:27], v[68:71], v[202:205], v[24:27]
	v_mfma_f32_16x16x32_bf16 v[28:31], v[72:75], v[198:201], v[28:31]
	v_mfma_f32_16x16x32_bf16 v[28:31], v[146:149], v[202:205], v[28:31]
	v_mfma_f32_16x16x32_bf16 v[8:11], v[64:67], v[206:209], v[8:11]
	v_mfma_f32_16x16x32_bf16 v[8:11], v[68:71], v[210:213], v[8:11]
	v_mfma_f32_16x16x32_bf16 v[12:15], v[72:75], v[206:209], v[12:15]
	v_mfma_f32_16x16x32_bf16 v[12:15], v[146:149], v[210:213], v[12:15]
	s_setprio 0
	s_setprio 1
	v_mfma_f32_16x16x32_bf16 v[52:55], v[150:153], v[174:177], v[52:55]
	v_mfma_f32_16x16x32_bf16 v[52:55], v[154:157], v[178:181], v[52:55]
	v_mfma_f32_16x16x32_bf16 v[48:51], v[158:161], v[174:177], v[48:51]
	v_mfma_f32_16x16x32_bf16 v[48:51], v[170:173], v[178:181], v[48:51]
	v_mfma_f32_16x16x32_bf16 v[36:39], v[150:153], v[182:185], v[36:39]
	v_mfma_f32_16x16x32_bf16 v[36:39], v[154:157], v[194:197], v[36:39]
	v_mfma_f32_16x16x32_bf16 v[32:35], v[158:161], v[182:185], v[32:35]
	v_mfma_f32_16x16x32_bf16 v[32:35], v[170:173], v[194:197], v[32:35]
	v_mfma_f32_16x16x32_bf16 v[20:23], v[150:153], v[198:201], v[20:23]
	v_mfma_f32_16x16x32_bf16 v[20:23], v[154:157], v[202:205], v[20:23]
	v_mfma_f32_16x16x32_bf16 v[16:19], v[158:161], v[198:201], v[16:19]
	v_mfma_f32_16x16x32_bf16 v[16:19], v[170:173], v[202:205], v[16:19]
	v_mfma_f32_16x16x32_bf16 v[4:7], v[150:153], v[206:209], v[4:7]
	v_mfma_f32_16x16x32_bf16 v[4:7], v[154:157], v[210:213], v[4:7]
	v_mfma_f32_16x16x32_bf16 v[0:3], v[158:161], v[206:209], v[0:3]
	v_mfma_f32_16x16x32_bf16 v[0:3], v[170:173], v[210:213], v[0:3]
	s_setprio 0
	s_barrier
; __device__ __forceinline__ float silu_f(float x) { return x * __builtin_amdgcn_rcpf(1.f + __expf(-x)); }
; #define PG8_BAR __builtin_amdgcn_s_barrier()
;     __device__ __forceinline__ void operator()(const f32x4 (&acc)[2][2][4][2], const Unit& u, int wr, int wc, int fr, int fq) const {
;         const int r0 = u.pm * BM + wr * 64 + fr, ch = 64 * u.pn + 16 * wc + 4 * fq, lane = fq * 16 + fr;
;         float rstd[2][4];
; #pragma unroll
;         for (int ai = 0; ai < 2; ++ai)
; #pragma unroll
;             for (int m = 0; m < 4; ++m) rstd[ai][m] = (float)ss[r0 + ai * HALF + m * 16] * (1.f / 16777216.f);
;         const f32x4 w0 = *(const f32x4*)(cw + ch), w1 = *(const f32x4*)(cw + 2048 + ch), w2 = *(const f32x4*)(cw + 4096 + ch);
;         const bool fuse = u.pm != 96;
;         const int lr = (lane & 48) | ((fr + 15) & 15), ll = (lane & 48) | ((fr + 1) & 15);
; #pragma unroll
;         for (int ai = 0; ai < 2; ++ai) {
;             f32x4 g[4], cu[4];
; #pragma unroll
;             for (int m = 0; m < 4; ++m) {
;                 const float rs = __builtin_amdgcn_rsqf(rstd[ai][m] * (1.f / 2048.f) + 1e-6f);
;                 const f32x4 b = acc[ai][0][m][0] * rs, z = acc[ai][0][m][1] * rs, c = acc[ai][1][m][0] * rs, uu = acc[ai][1][m][1] * rs;
; #pragma unroll
;                 for (int j = 0; j < 4; ++j) { g[m][j] = b[j] * silu_f(z[j]); cu[m][j] = c[j] * uu[j]; }
; template <class Epi, class Sched, bool ALIGN_EPI = false, bool SP2 = false>
; __device__ __forceinline__ void gemm_phase(PG8_LAS unsigned char* lds, const Gemm g, const Sched& S, const Epi& E) {
;     ...
;         if constexpr (ALIGN_EPI) { if (wr == 0) PG8_BAR; }
	s_add_i32 s95, s95, 2
	s_add_u32 vcc_lo, vcc_lo, 0x100
	s_addc_u32 vcc_hi, vcc_hi, 0
	s_add_u32 s3, s3, 0x100
	s_addc_u32 s94, s94, 0
	s_cmp_gt_u32 s95, 29
	s_cbranch_scc0 .LBB0_298
	v_lshl_add_u32 v148, s72, 8, v164
	v_ashrrev_i32_e32 v149, 31, v148
	v_lshl_add_u64 v[64:65], v[148:149], 3, s[92:93]
	global_load_dwordx2 v[66:67], v[64:65], off
	global_load_dwordx2 v[194:195], v[64:65], off offset:128
	global_load_dwordx2 v[196:197], v[64:65], off offset:256
	global_load_dwordx2 v[198:199], v[64:65], off offset:384
	s_and_b64 vcc, exec, s[58:59]
	s_cbranch_vccz .LBB0_301
	s_barrier
.LBB0_301:
	v_lshl_or_b32 v146, s64, 6, v166
	v_ashrrev_i32_e32 v147, 31, v146
	v_lshlrev_b64 v[72:73], 2, v[146:147]
	s_cmpk_lg_i32 s72, 0x60
	v_or_b32_e32 v150, 16, v148
	v_or_b32_e32 v154, 32, v148
	v_or_b32_e32 v160, 48, v148
	s_cselect_b64 s[72:73], -1, 0
	v_ashrrev_i32_e32 v151, 31, v150
	v_ashrrev_i32_e32 v155, 31, v154
	v_ashrrev_i32_e32 v161, 31, v160
	s_and_b64 vcc, exec, s[72:73]
	s_movk_i32 s94, 0x5fff
	s_waitcnt vmcnt(3)
	v_ffbh_u32_e32 v68, v67
	v_min_u32_e32 v68, 32, v68
	v_lshlrev_b64 v[66:67], v68, v[66:67]
	v_min_u32_e32 v66, 1, v66
	v_or_b32_e32 v66, v67, v66
	v_cvt_f32_u32_e32 v66, v66
	v_sub_u32_e32 v67, 32, v68
	v_ldexp_f32 v66, v66, v67
	v_mul_f32_e32 v173, 0x33800000, v66
	v_fmamk_f32 v173, v173, 0x3a000000, v227
	v_rsq_f32_e32 v173, v173
	s_waitcnt vmcnt(2)
	v_ffbh_u32_e32 v68, v195
	v_min_u32_e32 v68, 32, v68
	v_lshlrev_b64 v[194:195], v68, v[194:195]
	v_min_u32_e32 v194, 1, v194
	v_or_b32_e32 v194, v195, v194
	v_cvt_f32_u32_e32 v194, v194
	v_sub_u32_e32 v195, 32, v68
	v_mul_f32_e32 v132, v132, v173
	v_mul_f32_e32 v174, 0xbfb8aa3b, v132
	v_ldexp_f32 v194, v194, v195
	v_mul_f32_e32 v172, 0x33800000, v194
	v_exp_f32_e32 v174, v174
	v_mul_f32_e32 v136, v136, v173
	v_mul_f32_e32 v133, v133, v173
	v_mul_f32_e32 v128, v128, v173
	v_add_f32_e32 v174, 1.0, v174
	v_rcp_f32_e32 v174, v174
	v_mul_f32_e32 v124, v124, v173
	v_mul_f32_e32 v124, v128, v124
	v_mul_f32_e32 v128, v137, v173
	v_mul_f32_e32 v132, v132, v174
	v_mul_f32_e32 v132, v136, v132
	v_mul_f32_e32 v136, 0xbfb8aa3b, v133
	v_exp_f32_e32 v136, v136
	v_mul_f32_e32 v129, v129, v173
	v_mul_f32_e32 v125, v125, v173
	v_mul_f32_e32 v125, v129, v125
	v_add_f32_e32 v136, 1.0, v136
	v_rcp_f32_e32 v136, v136
	v_mul_f32_e32 v129, v138, v173
	v_mul_f32_e32 v131, v131, v173
	v_mul_f32_e32 v127, v127, v173
	v_mul_f32_e32 v133, v133, v136
	v_mul_f32_e32 v128, v128, v133
	v_mul_f32_e32 v133, v134, v173
	v_mul_f32_e32 v134, 0xbfb8aa3b, v133
	v_exp_f32_e32 v134, v134
	v_mul_f32_e32 v127, v131, v127
	v_fmamk_f32 v131, v172, 0x3a000000, v227
	v_rsq_f32_e32 v131, v131
	v_add_f32_e32 v134, 1.0, v134
	v_rcp_f32_e32 v134, v134
	v_mul_f32_e32 v130, v130, v173
	v_mul_f32_e32 v126, v126, v173
	v_mul_f32_e32 v126, v130, v126
	v_mul_f32_e32 v133, v133, v134
	v_mul_f32_e32 v129, v129, v133
	v_mul_f32_e32 v133, v135, v173
	v_mul_f32_e32 v134, 0xbfb8aa3b, v133
	v_exp_f32_e32 v134, v134
	v_mul_f32_e32 v130, v139, v173
	v_mul_f32_e32 v116, v116, v131
	v_mul_f32_e32 v120, v120, v131
	v_add_f32_e32 v134, 1.0, v134
	v_rcp_f32_e32 v134, v134
	v_mul_f32_e32 v117, v117, v131
	v_mul_f32_e32 v112, v112, v131
	v_mul_f32_e32 v108, v108, v131
	v_mul_f32_e32 v133, v133, v134
	v_mul_f32_e32 v130, v130, v133
	v_mul_f32_e32 v133, 0xbfb8aa3b, v116
	v_exp_f32_e32 v133, v133
	v_mul_f32_e32 v108, v112, v108
	v_mul_f32_e32 v112, v121, v131
	v_mul_f32_e32 v113, v113, v131
	v_add_f32_e32 v133, 1.0, v133
	v_rcp_f32_e32 v133, v133
	v_mul_f32_e32 v109, v109, v131
	v_mul_f32_e32 v109, v113, v109
	v_mul_f32_e32 v113, v122, v131
	v_mul_f32_e32 v116, v116, v133
	v_mul_f32_e32 v116, v120, v116
	v_mul_f32_e32 v120, 0xbfb8aa3b, v117
	v_exp_f32_e32 v120, v120
	v_mul_f32_e32 v115, v115, v131
	v_mul_f32_e32 v111, v111, v131
	v_mul_f32_e32 v111, v115, v111
	v_add_f32_e32 v120, 1.0, v120
	v_rcp_f32_e32 v120, v120
	v_mul_f32_e32 v114, v114, v131
	v_mul_f32_e32 v110, v110, v131
	v_mul_f32_e32 v110, v114, v110
	v_mul_f32_e32 v117, v117, v120
	v_mul_f32_e32 v112, v112, v117
	v_mul_f32_e32 v117, v118, v131
	v_mul_f32_e32 v118, 0xbfb8aa3b, v117
	v_exp_f32_e32 v118, v118
	v_mul_f32_e32 v114, v123, v131
	s_waitcnt vmcnt(1)
	v_ffbh_u32_e32 v68, v197
	v_min_u32_e32 v68, 32, v68
	v_lshlrev_b64 v[196:197], v68, v[196:197]
	v_min_u32_e32 v196, 1, v196
	v_or_b32_e32 v196, v197, v196
	v_cvt_f32_u32_e32 v196, v196
	v_sub_u32_e32 v197, 32, v68
	v_add_f32_e32 v118, 1.0, v118
	v_rcp_f32_e32 v118, v118
	v_ldexp_f32 v196, v196, v197
	v_mul_f32_e32 v171, 0x33800000, v196
	v_mul_f32_e32 v117, v117, v118
	v_mul_f32_e32 v113, v113, v117
	v_mul_f32_e32 v117, v119, v131
	v_mul_f32_e32 v118, 0xbfb8aa3b, v117
	v_exp_f32_e32 v118, v118
	v_fmamk_f32 v115, v171, 0x3a000000, v227
	v_rsq_f32_e32 v115, v115
	global_load_dwordx2 v[162:163], v[64:65], off offset:1024
	global_load_dwordx2 v[158:159], v[64:65], off offset:1152
	global_load_dwordx2 v[156:157], v[64:65], off offset:1280
	global_load_dwordx2 v[152:153], v[64:65], off offset:1408
	v_add_f32_e32 v118, 1.0, v118
	v_rcp_f32_e32 v118, v118
	v_mul_f32_e32 v100, v100, v115
	v_mul_f32_e32 v104, v104, v115
	v_mul_f32_e32 v96, v96, v115
	v_mul_f32_e32 v117, v117, v118
	v_mul_f32_e32 v114, v114, v117
	v_mul_f32_e32 v117, 0xbfb8aa3b, v100
	v_exp_f32_e32 v117, v117
	v_mul_f32_e32 v92, v92, v115
	v_mul_f32_e32 v93, v93, v115
	v_lshl_add_u64 v[64:65], s[56:57], 0, v[72:73]
	v_add_f32_e32 v117, 1.0, v117
	v_rcp_f32_e32 v117, v117
	s_waitcnt vmcnt(4)
; __device__ __forceinline__ unsigned cvt_pk_bf16(float lo, float hi) { unsigned r; asm volatile("v_cvt_pk_bf16_f32 %0, %1, %2" : "=v"(r) : "v"(lo), "v"(hi)); return r; }
; __device__ __forceinline__ float silu_f(float x) { return x * __builtin_amdgcn_rcpf(1.f + __expf(-x)); }
;     __device__ __forceinline__ void operator()(const f32x4 (&acc)[2][2][4][2], const Unit& u, int wr, int wc, int fr, int fq) const {
;     ...
;                 const float rs = __builtin_amdgcn_rsqf(rstd[ai][m] * (1.f / 2048.f) + 1e-6f);
;                 const f32x4 b = acc[ai][0][m][0] * rs, z = acc[ai][0][m][1] * rs, c = acc[ai][1][m][0] * rs, uu = acc[ai][1][m][1] * rs;
; #pragma unroll
;                 for (int j = 0; j < 4; ++j) { g[m][j] = b[j] * silu_f(z[j]); cu[m][j] = c[j] * uu[j]; }
;             }
;             if (fuse) {
;                 f32x4 R[4], L[4];
; #pragma unroll
;                 for (int m = 0; m < 4; ++m)
; #pragma unroll
;                     for (int j = 0; j < 4; ++j) { R[m][j] = __shfl(cu[m][j], lr); L[m][j] = __shfl(cu[m][j], ll); }
; #pragma unroll
;                 for (int m = 0; m < 4; ++m) {
;                     const int r = r0 + ai * HALF + m * 16;
;                     const f32x4 prev = (fr == 0) ? R[m > 0 ? m - 1 : 0] : R[m], next = (fr == 15) ? L[m < 3 ? m + 1 : 3] : L[m];
;                     const bool edge = (m == 0 && fr == 0) || (m == 3 && fr == 15);
;                     f32x4 y;
; #pragma unroll
;                     for (int j = 0; j < 4; ++j) { const float t = g[m][j] * (prev[j] * w0[j] + cu[m][j] * w1[j] + next[j] * w2[j]); y[j] = edge ? g[m][j] : t; }
;                     const size_t off = (size_t)r * 2048 + ch;
;                     u32x2 o1; o1.x = cvt_pk_bf16(y[0], y[1]); o1.y = cvt_pk_bf16(y[2], y[3]);
;                     *(u32x2*)(G + off) = o1;
	v_ffbh_u32_e32 v68, v199
	v_mul_f32_e32 v100, v100, v117
	v_mul_f32_e32 v104, v104, v100
	v_mul_f32_e32 v100, v96, v92
	v_mul_f32_e32 v96, v101, v115
	v_mul_f32_e32 v101, 0xbfb8aa3b, v96
	v_exp_f32_e32 v101, v101
	v_min_u32_e32 v68, 32, v68
	v_lshlrev_b64 v[198:199], v68, v[198:199]
	v_min_u32_e32 v198, 1, v198
	v_add_f32_e32 v101, 1.0, v101
	v_rcp_f32_e32 v101, v101
	v_or_b32_e32 v198, v199, v198
	v_cvt_f32_u32_e32 v198, v198
	v_mul_f32_e32 v92, v105, v115
	v_mul_f32_e32 v96, v96, v101
	v_sub_u32_e32 v199, 32, v68
	v_mul_f32_e32 v105, v92, v96
	v_mul_f32_e32 v92, v97, v115
	v_ldexp_f32 v198, v198, v199
	v_lshl_add_u64 v[68:69], s[60:61], 0, v[72:73]
	v_lshl_add_u64 v[72:73], s[62:63], 0, v[72:73]
	v_mul_f32_e32 v101, v92, v93
	v_mul_f32_e32 v93, v102, v115
	v_mul_f32_e32 v170, 0x33800000, v198
	global_load_dwordx4 v[64:67], v[64:65], off
	v_mul_f32_e32 v96, 0xbfb8aa3b, v93
	global_load_dwordx4 v[68:71], v[68:69], off
	v_exp_f32_e32 v96, v96
	global_load_dwordx4 v[72:75], v[72:73], off
	v_mul_f32_e32 v92, v106, v115
	v_add_f32_e32 v96, 1.0, v96
	v_rcp_f32_e32 v96, v96
	s_nop 0
	v_mul_f32_e32 v93, v93, v96
	v_mul_f32_e32 v102, v92, v93
	v_mul_f32_e32 v92, v98, v115
	v_mul_f32_e32 v93, v94, v115
	v_mul_f32_e32 v98, v92, v93
	v_mul_f32_e32 v93, v103, v115
	v_mul_f32_e32 v94, 0xbfb8aa3b, v93
	v_exp_f32_e32 v94, v94
	v_mul_f32_e32 v92, v107, v115
	v_add_f32_e32 v94, 1.0, v94
	v_rcp_f32_e32 v94, v94
	s_nop 0
	v_mul_f32_e32 v93, v93, v94
	v_mul_f32_e32 v103, v92, v93
	v_mul_f32_e32 v92, v99, v115
	v_mul_f32_e32 v93, v95, v115
	v_mul_f32_e32 v99, v92, v93
	v_fmamk_f32 v92, v170, 0x3a000000, v227
	v_rsq_f32_e32 v92, v92
	s_nop 0
	v_mul_f32_e32 v84, v84, v92
	v_mul_f32_e32 v93, 0xbfb8aa3b, v84
	v_exp_f32_e32 v93, v93
	v_mul_f32_e32 v80, v80, v92
	v_mul_f32_e32 v76, v76, v92
	v_mul_f32_e32 v88, v88, v92
	v_add_f32_e32 v93, 1.0, v93
	v_rcp_f32_e32 v93, v93
	v_mul_f32_e32 v77, v77, v92
	v_mul_f32_e32 v78, v78, v92
	v_mul_f32_e32 v84, v84, v93
	v_mul_f32_e32 v93, v80, v76
	v_mul_f32_e32 v80, v85, v92
	v_mul_f32_e32 v106, v88, v84
	v_mul_f32_e32 v84, 0xbfb8aa3b, v80
	v_exp_f32_e32 v84, v84
	v_mul_f32_e32 v76, v89, v92
	v_add_f32_e32 v84, 1.0, v84
	v_rcp_f32_e32 v84, v84
	s_nop 0
	v_mul_f32_e32 v80, v80, v84
	v_mul_f32_e32 v107, v76, v80
	v_mul_f32_e32 v80, v86, v92
	v_mul_f32_e32 v76, v81, v92
	v_mul_f32_e32 v81, 0xbfb8aa3b, v80
	v_exp_f32_e32 v81, v81
	v_mul_f32_e32 v77, v76, v77
	v_mul_f32_e32 v76, v90, v92
	v_add_f32_e32 v81, 1.0, v81
	v_rcp_f32_e32 v81, v81
	s_nop 0
	v_mul_f32_e32 v80, v80, v81
	v_mul_f32_e32 v115, v76, v80
	v_mul_f32_e32 v76, v82, v92
	v_mul_f32_e32 v81, v76, v78
	v_mul_f32_e32 v78, v87, v92
	v_mul_f32_e32 v80, 0xbfb8aa3b, v78
	v_exp_f32_e32 v80, v80
	v_mul_f32_e32 v76, v91, v92
	v_add_f32_e32 v80, 1.0, v80
	v_rcp_f32_e32 v80, v80
	s_nop 0
	v_mul_f32_e32 v78, v78, v80
	v_mul_f32_e32 v117, v76, v78
	v_mul_f32_e32 v76, v83, v92
	v_mul_f32_e32 v78, v79, v92
	v_lshlrev_b64 v[82:83], 11, v[148:149]
	v_mul_f32_e32 v79, v76, v78
	v_lshl_add_u64 v[82:83], v[82:83], 0, v[146:147]
	s_cbranch_vccz .LBB0_307
	v_and_b32_e32 v76, 64, v232
	v_or_b32_e32 v78, v76, v167
	v_or_b32_e32 v76, v76, v168
	v_lshlrev_b32_e32 v78, 2, v78
	v_lshlrev_b32_e32 v84, 2, v76
	s_nop 1
	v_mov_b32_dpp v88, v124 row_ror:1 row_mask:0xf bank_mask:0xf
	v_mov_b32_dpp v85, v124 row_ror:15 row_mask:0xf bank_mask:0xf
	v_mov_b32_dpp v86, v125 row_ror:15 row_mask:0xf bank_mask:0xf
	v_mov_b32_dpp v87, v126 row_ror:15 row_mask:0xf bank_mask:0xf
	v_mov_b32_dpp v171, v108 row_ror:15 row_mask:0xf bank_mask:0xf
	v_mov_b32_dpp v172, v109 row_ror:15 row_mask:0xf bank_mask:0xf
	v_mov_b32_dpp v173, v110 row_ror:15 row_mask:0xf bank_mask:0xf
	v_mov_b32_dpp v89, v125 row_ror:1 row_mask:0xf bank_mask:0xf
	v_mov_b32_dpp v96, v126 row_ror:1 row_mask:0xf bank_mask:0xf
	v_mov_b32_dpp v97, v127 row_ror:1 row_mask:0xf bank_mask:0xf
	v_mov_b32_dpp v90, v127 row_ror:15 row_mask:0xf bank_mask:0xf
	v_mov_b32_dpp v134, v108 row_ror:1 row_mask:0xf bank_mask:0xf
	v_mov_b32_dpp v135, v109 row_ror:1 row_mask:0xf bank_mask:0xf
	v_mov_b32_dpp v137, v110 row_ror:1 row_mask:0xf bank_mask:0xf
	v_mov_b32_dpp v139, v111 row_ror:1 row_mask:0xf bank_mask:0xf
	v_mov_b32_dpp v174, v111 row_ror:15 row_mask:0xf bank_mask:0xf
	v_mov_b32_dpp v118, v100 row_ror:1 row_mask:0xf bank_mask:0xf
	v_mov_b32_dpp v136, v100 row_ror:15 row_mask:0xf bank_mask:0xf
	v_mov_b32_dpp v119, v101 row_ror:1 row_mask:0xf bank_mask:0xf
	v_mov_b32_dpp v138, v101 row_ror:15 row_mask:0xf bank_mask:0xf
	v_mov_b32_dpp v120, v98 row_ror:1 row_mask:0xf bank_mask:0xf
	v_mov_b32_dpp v149, v98 row_ror:15 row_mask:0xf bank_mask:0xf
	v_mov_b32_dpp v122, v99 row_ror:1 row_mask:0xf bank_mask:0xf
	v_mov_b32_dpp v170, v99 row_ror:15 row_mask:0xf bank_mask:0xf
	v_mov_b32_dpp v121, v93 row_ror:1 row_mask:0xf bank_mask:0xf
	v_mov_b32_dpp v92, v93 row_ror:15 row_mask:0xf bank_mask:0xf
	v_mov_b32_dpp v123, v77 row_ror:1 row_mask:0xf bank_mask:0xf
	v_mov_b32_dpp v76, v77 row_ror:15 row_mask:0xf bank_mask:0xf
	v_mov_b32_dpp v131, v81 row_ror:1 row_mask:0xf bank_mask:0xf
	v_mov_b32_dpp v80, v81 row_ror:15 row_mask:0xf bank_mask:0xf
	v_mov_b32_dpp v133, v79 row_ror:1 row_mask:0xf bank_mask:0xf
	v_mov_b32_dpp v78, v79 row_ror:15 row_mask:0xf bank_mask:0xf
	s_waitcnt lgkmcnt(14)
	v_cndmask_b32_e64 v95, v87, v173, s[6:7]
	v_cndmask_b32_e64 v91, v86, v172, s[6:7]
	v_cndmask_b32_e64 v87, v85, v171, s[6:7]
	s_waitcnt vmcnt(2)
	v_mov_b32_e32 v84, v64
	s_waitcnt vmcnt(0)
	v_mov_b32_e32 v85, v72
	v_mov_b32_e32 v86, v88
	v_pk_mul_f32 v[86:87], v[84:85], v[86:87]
	v_cndmask_b32_e64 v177, v90, v174, s[6:7]
	v_fma_f32 v86, v124, v68, v86
	v_add_f32_e32 v86, v86, v87
	v_mul_f32_e32 v86, v132, v86
	v_cndmask_b32_e64 v175, v86, v132, s[4:5]
	v_mov_b32_e32 v86, v65
	v_mov_b32_e32 v87, v73
	v_mov_b32_e32 v90, v89
	v_pk_mul_f32 v[90:91], v[86:87], v[90:91]
	v_mov_b32_e32 v94, v96
	v_fma_f32 v90, v125, v69, v90
	v_add_f32_e32 v90, v90, v91
	v_mul_f32_e32 v90, v128, v90
	v_cndmask_b32_e64 v178, v90, v128, s[4:5]
	v_mov_b32_e32 v90, v66
	v_mov_b32_e32 v91, v74
	v_pk_mul_f32 v[94:95], v[90:91], v[94:95]
	v_mov_b32_e32 v176, v97
	v_fma_f32 v94, v126, v70, v94
	v_add_f32_e32 v94, v94, v95
	v_mul_f32_e32 v94, v129, v94
	v_cndmask_b32_e64 v179, v94, v129, s[4:5]
	v_mov_b32_e32 v94, v67
	v_mov_b32_e32 v95, v75
	v_pk_mul_f32 v[176:177], v[94:95], v[176:177]
	s_nop 0
	v_fma_f32 v176, v127, v71, v176
	v_add_f32_e32 v176, v176, v177
	v_mul_f32_e32 v176, v130, v176
	v_cndmask_b32_e64 v177, v176, v130, s[4:5]
	v_cvt_pk_bf16_f32 v176, v175, v178
	v_cvt_pk_bf16_f32 v177, v179, v177
	v_lshl_add_u64 v[178:179], v[82:83], 1, s[48:49]
	global_store_dwordx2 v[178:179], v[176:177], off
	s_and_saveexec_b64 s[64:65], s[8:9]
	s_cbranch_execz .LBB0_304
	v_lshl_add_u64 v[178:179], v[82:83], 1, s[16:17]
	v_cvt_pk_bf16_f32 v176, v124, v125
	v_cvt_pk_bf16_f32 v177, v126, v127
	global_store_dwordx2 v[178:179], v[176:177], off

; #define PG8_STAGE(bufoff, gbase, voff) do { _Pragma("unroll") for (int _i = 0; _i < 2; ++_i) \
;         __builtin_amdgcn_global_load_lds((const unsigned*)((const char*)(gbase) + (voff)[_i]), (PG8_LAS unsigned*)(lds + (bufoff) + ldsw + _i * 8192), 16, 0, 0); } while (0)
; #define PG8_LDA(dst, b, h) do { _Pragma("unroll") for (int m = 0; m < 4; ++m) _Pragma("unroll") for (int k = 0; k < 2; ++k) dst[m][k] = *(const PG8_LAS bf16x8*)(lds + PG8_SA(b, h) + aoff + m * 2048 + k * 1024); } while (0)
; #define PG8_LDB(dst, b, h) do { _Pragma("unroll") for (int n = 0; n < 2; ++n) _Pragma("unroll") for (int k = 0; k < 2; ++k) dst[n][k] = *(const PG8_LAS bf16x8*)(lds + PG8_SB(b, h) + boff + n * 2048 + k * 1024); } while (0)
; #define PG8_MMA(ai, bj, At, Bt) do { __builtin_amdgcn_s_setprio(1); _Pragma("unroll") for (int m = 0; m < 4; ++m) _Pragma("unroll") for (int n = 0; n < 2; ++n) _Pragma("unroll") for (int k = 0; k < 2; ++k) \
;         acc[ai][bj][m][n] = __builtin_amdgcn_mfma_f32_16x16x32_bf16(Bt[n][k], At[m][k], acc[ai][bj][m][n], 0, 0, 0); __builtin_amdgcn_s_setprio(0); } while (0)
; #define PG8_WAIT_V(n) asm volatile("s_waitcnt vmcnt(" #n ")" ::: "memory")
; #define PG8_WAIT_L(n) asm volatile("s_waitcnt lgkmcnt(" #n ")" ::: "memory")
; #define PG8_BAR __builtin_amdgcn_s_barrier()
; #define PG8_SCHED __builtin_amdgcn_sched_barrier(0)
; template <class Epi, class Sched, bool ALIGN_EPI = false, bool SP2 = false>
; __device__ __forceinline__ void gemm_phase(PG8_LAS unsigned char* lds, const Gemm g, const Sched& S, const Epi& E) {
;     ...
;             PG8_LDB(B0, 0, 0); PG8_LDB(B1, 0, 1); PG8_SCHED; PG8_LDA(At, 0, 0); PG8_STAGE(PG8_SA(1, 1), a1 + hstep, voffA);
;             PG8_WAIT_V(8); PG8_WAIT_L(0); PG8_BAR; PG8_MMA(0, 0, At, B0); PG8_MMA(0, 1, At, B1); PG8_BAR; PG8_SCHED;
;             PG8_LDA(At, 0, 1); PG8_STAGE(PG8_SB(0, 0), b2, voffB); PG8_STAGE(PG8_SB(0, 1), b2 + hstep, voffB); PG8_STAGE(PG8_SA(0, 0), a2, voffA);
;             PG8_WAIT_V(8); PG8_WAIT_L(0); PG8_BAR; PG8_MMA(1, 0, At, B0); PG8_MMA(1, 1, At, B1); PG8_BAR; PG8_SCHED;
.LBB0_344:
	s_add_u32 s10, s8, 0xfff80080
	s_addc_u32 s11, s9, -1
	s_add_i32 s36, 0, 0x10000
	s_cmp_eq_u32 s57, 28
	s_cselect_b32 s63, s7, s11
	s_cselect_b32 s62, s14, s10
	s_cselect_b32 s11, s15, s3
	s_cselect_b32 s10, s54, s55
	s_add_i32 s37, 0, 0x14000
	ds_read_b128 v[128:131], v218
	ds_read_b128 v[132:135], v218 offset:1024
	ds_read_b128 v[136:139], v218 offset:2048
	ds_read_b128 v[140:143], v218 offset:3072
	ds_read_b128 v[144:147], v218 offset:16384
	ds_read_b128 v[148:151], v218 offset:17408
	ds_read_b128 v[152:155], v218 offset:18432
	ds_read_b128 v[156:159], v218 offset:19456
	s_add_i32 m0, s53, 0xc000
	ds_read_b128 v[174:177], v204
	ds_read_b128 v[178:181], v204 offset:1024
	ds_read_b128 v[182:185], v204 offset:2048
	ds_read_b128 v[194:197], v204 offset:3072
	ds_read_b128 v[198:201], v204 offset:4096
	ds_read_b128 v[206:209], v204 offset:5120
	ds_read_b128 v[210:213], v204 offset:6144
	ds_read_b128 v[214:217], v204 offset:7168
	global_load_lds_dwordx4 v170, s[8:9]
	s_add_i32 m0, s53, 0xe000
	s_nop 0
	global_load_lds_dwordx4 v172, s[8:9]
	s_waitcnt vmcnt(8)
	s_waitcnt lgkmcnt(0)
	s_barrier
	s_setprio 1
	s_waitcnt lgkmcnt(0)
	v_mfma_f32_16x16x32_bf16 v[124:127], v[128:131], v[174:177], v[124:127]
	v_mfma_f32_16x16x32_bf16 v[124:127], v[132:135], v[178:181], v[124:127]
	v_mfma_f32_16x16x32_bf16 v[120:123], v[136:139], v[174:177], v[120:123]
	v_mfma_f32_16x16x32_bf16 v[120:123], v[140:143], v[178:181], v[120:123]
	v_mfma_f32_16x16x32_bf16 v[108:111], v[128:131], v[182:185], v[108:111]
	v_mfma_f32_16x16x32_bf16 v[108:111], v[132:135], v[194:197], v[108:111]
	v_mfma_f32_16x16x32_bf16 v[104:107], v[136:139], v[182:185], v[104:107]
	v_mfma_f32_16x16x32_bf16 v[104:107], v[140:143], v[194:197], v[104:107]
	v_mfma_f32_16x16x32_bf16 v[92:95], v[128:131], v[198:201], v[92:95]
	v_mfma_f32_16x16x32_bf16 v[92:95], v[132:135], v[206:209], v[92:95]
	v_mfma_f32_16x16x32_bf16 v[88:91], v[136:139], v[198:201], v[88:91]
	v_mfma_f32_16x16x32_bf16 v[88:91], v[140:143], v[206:209], v[88:91]
	v_mfma_f32_16x16x32_bf16 v[76:79], v[128:131], v[210:213], v[76:79]
	v_mfma_f32_16x16x32_bf16 v[76:79], v[132:135], v[214:217], v[76:79]
	v_mfma_f32_16x16x32_bf16 v[72:75], v[136:139], v[210:213], v[72:75]
	v_mfma_f32_16x16x32_bf16 v[72:75], v[140:143], v[214:217], v[72:75]
	s_setprio 0
	s_setprio 1
	v_mfma_f32_16x16x32_bf16 v[116:119], v[144:147], v[174:177], v[116:119]
	v_mfma_f32_16x16x32_bf16 v[116:119], v[148:151], v[178:181], v[116:119]
	v_mfma_f32_16x16x32_bf16 v[112:115], v[152:155], v[174:177], v[112:115]
	v_mfma_f32_16x16x32_bf16 v[112:115], v[156:159], v[178:181], v[112:115]
	v_mfma_f32_16x16x32_bf16 v[100:103], v[144:147], v[182:185], v[100:103]
	v_mfma_f32_16x16x32_bf16 v[100:103], v[148:151], v[194:197], v[100:103]
	v_mfma_f32_16x16x32_bf16 v[96:99], v[152:155], v[182:185], v[96:99]
	v_mfma_f32_16x16x32_bf16 v[96:99], v[156:159], v[194:197], v[96:99]
	v_mfma_f32_16x16x32_bf16 v[84:87], v[144:147], v[198:201], v[84:87]
	v_mfma_f32_16x16x32_bf16 v[84:87], v[148:151], v[206:209], v[84:87]
	v_mfma_f32_16x16x32_bf16 v[80:83], v[152:155], v[198:201], v[80:83]
	v_mfma_f32_16x16x32_bf16 v[80:83], v[156:159], v[206:209], v[80:83]
	v_mfma_f32_16x16x32_bf16 v[68:71], v[144:147], v[210:213], v[68:71]
	v_mfma_f32_16x16x32_bf16 v[68:71], v[148:151], v[214:217], v[68:71]
	v_mfma_f32_16x16x32_bf16 v[64:67], v[152:155], v[210:213], v[64:67]
	v_mfma_f32_16x16x32_bf16 v[64:67], v[156:159], v[214:217], v[64:67]
	s_setprio 0
	s_barrier
	s_add_i32 s36, s36, s70
	s_mov_b32 m0, s36
	ds_read_b128 v[174:177], v204 offset:16384
	ds_read_b128 v[178:181], v204 offset:17408
	ds_read_b128 v[182:185], v204 offset:18432
	ds_read_b128 v[194:197], v204 offset:19456
	ds_read_b128 v[198:201], v204 offset:20480
	ds_read_b128 v[206:209], v204 offset:21504
	ds_read_b128 v[210:213], v204 offset:22528
	ds_read_b128 v[214:217], v204 offset:23552
	global_load_lds_dwordx4 v160, s[10:11]
	s_add_i32 m0, s36, 0x2000
	s_add_u32 s64, s10, 0x80000
	s_addc_u32 s65, s11, 0
	s_add_i32 s36, s37, s70
	global_load_lds_dwordx4 v162, s[10:11]
	s_mov_b32 m0, s36
	s_nop 0
	global_load_lds_dwordx4 v160, s[64:65]
	s_add_i32 m0, s36, 0x2000
	s_nop 0
	global_load_lds_dwordx4 v162, s[64:65]
	s_mov_b32 m0, s53
	s_nop 0
	global_load_lds_dwordx4 v160, s[62:63]
	s_mov_b32 m0, s71
	s_nop 0
	global_load_lds_dwordx4 v162, s[62:63]
	s_waitcnt vmcnt(8)
	s_waitcnt lgkmcnt(0)
	s_barrier
	s_setprio 1
	s_waitcnt lgkmcnt(0)
	v_mfma_f32_16x16x32_bf16 v[60:63], v[128:131], v[174:177], v[60:63]
	v_mfma_f32_16x16x32_bf16 v[60:63], v[132:135], v[178:181], v[60:63]
	v_mfma_f32_16x16x32_bf16 v[56:59], v[136:139], v[174:177], v[56:59]
	v_mfma_f32_16x16x32_bf16 v[56:59], v[140:143], v[178:181], v[56:59]
	v_mfma_f32_16x16x32_bf16 v[44:47], v[128:131], v[182:185], v[44:47]
	v_mfma_f32_16x16x32_bf16 v[44:47], v[132:135], v[194:197], v[44:47]
	v_mfma_f32_16x16x32_bf16 v[40:43], v[136:139], v[182:185], v[40:43]
	v_mfma_f32_16x16x32_bf16 v[40:43], v[140:143], v[194:197], v[40:43]
	v_mfma_f32_16x16x32_bf16 v[28:31], v[128:131], v[198:201], v[28:31]
	v_mfma_f32_16x16x32_bf16 v[28:31], v[132:135], v[206:209], v[28:31]
	v_mfma_f32_16x16x32_bf16 v[24:27], v[136:139], v[198:201], v[24:27]
	v_mfma_f32_16x16x32_bf16 v[24:27], v[140:143], v[206:209], v[24:27]
	v_mfma_f32_16x16x32_bf16 v[12:15], v[128:131], v[210:213], v[12:15]
	v_mfma_f32_16x16x32_bf16 v[12:15], v[132:135], v[214:217], v[12:15]
	v_mfma_f32_16x16x32_bf16 v[8:11], v[136:139], v[210:213], v[8:11]
	v_mfma_f32_16x16x32_bf16 v[8:11], v[140:143], v[214:217], v[8:11]
	s_setprio 0
	s_setprio 1
	v_mfma_f32_16x16x32_bf16 v[52:55], v[144:147], v[174:177], v[52:55]
	v_mfma_f32_16x16x32_bf16 v[52:55], v[148:151], v[178:181], v[52:55]
	v_mfma_f32_16x16x32_bf16 v[48:51], v[152:155], v[174:177], v[48:51]
	v_mfma_f32_16x16x32_bf16 v[48:51], v[156:159], v[178:181], v[48:51]
	v_mfma_f32_16x16x32_bf16 v[36:39], v[144:147], v[182:185], v[36:39]
	v_mfma_f32_16x16x32_bf16 v[36:39], v[148:151], v[194:197], v[36:39]
	v_mfma_f32_16x16x32_bf16 v[32:35], v[152:155], v[182:185], v[32:35]
	v_mfma_f32_16x16x32_bf16 v[32:35], v[156:159], v[194:197], v[32:35]
	v_mfma_f32_16x16x32_bf16 v[20:23], v[144:147], v[198:201], v[20:23]
	v_mfma_f32_16x16x32_bf16 v[20:23], v[148:151], v[206:209], v[20:23]
	v_mfma_f32_16x16x32_bf16 v[16:19], v[152:155], v[198:201], v[16:19]
	v_mfma_f32_16x16x32_bf16 v[16:19], v[156:159], v[206:209], v[16:19]
	v_mfma_f32_16x16x32_bf16 v[4:7], v[144:147], v[210:213], v[4:7]
	v_mfma_f32_16x16x32_bf16 v[4:7], v[148:151], v[214:217], v[4:7]
	v_mfma_f32_16x16x32_bf16 v[0:3], v[152:155], v[210:213], v[0:3]
	v_mfma_f32_16x16x32_bf16 v[0:3], v[156:159], v[214:217], v[0:3]
	s_setprio 0
	s_barrier
; #define PG8_STAGE(bufoff, gbase, voff) do { _Pragma("unroll") for (int _i = 0; _i < 2; ++_i) \
;         __builtin_amdgcn_global_load_lds((const unsigned*)((const char*)(gbase) + (voff)[_i]), (PG8_LAS unsigned*)(lds + (bufoff) + ldsw + _i * 8192), 16, 0, 0); } while (0)
; #define PG8_LDA(dst, b, h) do { _Pragma("unroll") for (int m = 0; m < 4; ++m) _Pragma("unroll") for (int k = 0; k < 2; ++k) dst[m][k] = *(const PG8_LAS bf16x8*)(lds + PG8_SA(b, h) + aoff + m * 2048 + k * 1024); } while (0)
; #define PG8_LDB(dst, b, h) do { _Pragma("unroll") for (int n = 0; n < 2; ++n) _Pragma("unroll") for (int k = 0; k < 2; ++k) dst[n][k] = *(const PG8_LAS bf16x8*)(lds + PG8_SB(b, h) + boff + n * 2048 + k * 1024); } while (0)
; #define PG8_MMA(ai, bj, At, Bt) do { __builtin_amdgcn_s_setprio(1); _Pragma("unroll") for (int m = 0; m < 4; ++m) _Pragma("unroll") for (int n = 0; n < 2; ++n) _Pragma("unroll") for (int k = 0; k < 2; ++k) \
;         acc[ai][bj][m][n] = __builtin_amdgcn_mfma_f32_16x16x32_bf16(Bt[n][k], At[m][k], acc[ai][bj][m][n], 0, 0, 0); __builtin_amdgcn_s_setprio(0); } while (0)
; #define PG8_WAIT_V(n) asm volatile("s_waitcnt vmcnt(" #n ")" ::: "memory")
; #define PG8_WAIT_L(n) asm volatile("s_waitcnt lgkmcnt(" #n ")" ::: "memory")
; #define PG8_BAR __builtin_amdgcn_s_barrier()
; #define PG8_SCHED __builtin_amdgcn_sched_barrier(0)
; template <class Epi, class Sched, bool ALIGN_EPI = false, bool SP2 = false>
; __device__ __forceinline__ void gemm_phase(PG8_LAS unsigned char* lds, const Gemm g, const Sched& S, const Epi& E) {
;     ...
;             PG8_LDB(B0, 1, 0); PG8_LDB(B1, 1, 1); PG8_SCHED; PG8_LDA(At, 1, 0); PG8_STAGE(PG8_SA(0, 1), a2 + hstep, voffA);
;             PG8_WAIT_V(8); PG8_WAIT_L(0); PG8_BAR; PG8_MMA(0, 0, At, B0); PG8_MMA(0, 1, At, B1); PG8_BAR; PG8_SCHED;
;             PG8_LDA(At, 1, 1); PG8_STAGE(PG8_SB(1, 0), b3, voffB); PG8_STAGE(PG8_SB(1, 1), b3 + hstep, voffB); PG8_STAGE(PG8_SA(1, 0), a3, voffA);
	s_add_i32 s36, 0, 0x18000
	s_add_i32 s37, 0, 0x1c000
	ds_read_b128 v[128:131], v218 offset:32768
	ds_read_b128 v[132:135], v218 offset:33792
	ds_read_b128 v[136:139], v218 offset:34816
	ds_read_b128 v[140:143], v218 offset:35840
	ds_read_b128 v[144:147], v218 offset:49152
	ds_read_b128 v[148:151], v218 offset:50176
	ds_read_b128 v[152:155], v218 offset:51200
	ds_read_b128 v[156:159], v218 offset:52224
	s_add_u32 s62, s62, 0x80000
	s_addc_u32 s63, s63, 0
	s_mov_b32 m0, s72
	ds_read_b128 v[174:177], v204 offset:32768
	ds_read_b128 v[178:181], v204 offset:33792
	ds_read_b128 v[182:185], v204 offset:34816
	ds_read_b128 v[194:197], v204 offset:35840
	ds_read_b128 v[198:201], v204 offset:36864
	ds_read_b128 v[206:209], v204 offset:37888
	ds_read_b128 v[210:213], v204 offset:38912
	ds_read_b128 v[214:217], v204 offset:39936
	global_load_lds_dwordx4 v160, s[62:63]
	s_mov_b32 m0, s73
	s_nop 0
	global_load_lds_dwordx4 v162, s[62:63]
	s_waitcnt vmcnt(8)
	s_waitcnt lgkmcnt(0)
	s_barrier
	s_setprio 1
	s_waitcnt lgkmcnt(0)
	v_mfma_f32_16x16x32_bf16 v[124:127], v[128:131], v[174:177], v[124:127]
	v_mfma_f32_16x16x32_bf16 v[124:127], v[132:135], v[178:181], v[124:127]
	v_mfma_f32_16x16x32_bf16 v[120:123], v[136:139], v[174:177], v[120:123]
	v_mfma_f32_16x16x32_bf16 v[120:123], v[140:143], v[178:181], v[120:123]
	v_mfma_f32_16x16x32_bf16 v[108:111], v[128:131], v[182:185], v[108:111]
	v_mfma_f32_16x16x32_bf16 v[108:111], v[132:135], v[194:197], v[108:111]
	v_mfma_f32_16x16x32_bf16 v[104:107], v[136:139], v[182:185], v[104:107]
	v_mfma_f32_16x16x32_bf16 v[104:107], v[140:143], v[194:197], v[104:107]
	v_mfma_f32_16x16x32_bf16 v[92:95], v[128:131], v[198:201], v[92:95]
	v_mfma_f32_16x16x32_bf16 v[92:95], v[132:135], v[206:209], v[92:95]
	v_mfma_f32_16x16x32_bf16 v[88:91], v[136:139], v[198:201], v[88:91]
	v_mfma_f32_16x16x32_bf16 v[88:91], v[140:143], v[206:209], v[88:91]
	v_mfma_f32_16x16x32_bf16 v[76:79], v[128:131], v[210:213], v[76:79]
	v_mfma_f32_16x16x32_bf16 v[76:79], v[132:135], v[214:217], v[76:79]
	v_mfma_f32_16x16x32_bf16 v[72:75], v[136:139], v[210:213], v[72:75]
	v_mfma_f32_16x16x32_bf16 v[72:75], v[140:143], v[214:217], v[72:75]
	s_setprio 0
	s_setprio 1
	v_mfma_f32_16x16x32_bf16 v[116:119], v[144:147], v[174:177], v[116:119]
	v_mfma_f32_16x16x32_bf16 v[116:119], v[148:151], v[178:181], v[116:119]
	v_mfma_f32_16x16x32_bf16 v[112:115], v[152:155], v[174:177], v[112:115]
	v_mfma_f32_16x16x32_bf16 v[112:115], v[156:159], v[178:181], v[112:115]
	v_mfma_f32_16x16x32_bf16 v[100:103], v[144:147], v[182:185], v[100:103]
	v_mfma_f32_16x16x32_bf16 v[100:103], v[148:151], v[194:197], v[100:103]
	v_mfma_f32_16x16x32_bf16 v[96:99], v[152:155], v[182:185], v[96:99]
	v_mfma_f32_16x16x32_bf16 v[96:99], v[156:159], v[194:197], v[96:99]
	v_mfma_f32_16x16x32_bf16 v[84:87], v[144:147], v[198:201], v[84:87]
	v_mfma_f32_16x16x32_bf16 v[84:87], v[148:151], v[206:209], v[84:87]
	v_mfma_f32_16x16x32_bf16 v[80:83], v[152:155], v[198:201], v[80:83]
	v_mfma_f32_16x16x32_bf16 v[80:83], v[156:159], v[206:209], v[80:83]
	v_mfma_f32_16x16x32_bf16 v[68:71], v[144:147], v[210:213], v[68:71]
	v_mfma_f32_16x16x32_bf16 v[68:71], v[148:151], v[214:217], v[68:71]
	v_mfma_f32_16x16x32_bf16 v[64:67], v[152:155], v[210:213], v[64:67]
	v_mfma_f32_16x16x32_bf16 v[64:67], v[156:159], v[214:217], v[64:67]
	s_setprio 0
	s_barrier
	s_add_i32 s36, s36, s70
	s_mov_b32 m0, s36
	ds_read_b128 v[174:177], v204 offset:49152
	ds_read_b128 v[178:181], v204 offset:50176
	ds_read_b128 v[182:185], v204 offset:51200
	ds_read_b128 v[194:197], v204 offset:52224
	ds_read_b128 v[198:201], v204 offset:53248
	ds_read_b128 v[206:209], v204 offset:54272
	ds_read_b128 v[210:213], v204 offset:55296
	ds_read_b128 v[214:217], v204 offset:56320
	s_add_u32 s100, s10, 0x80
	s_addc_u32 s101, s11, 0
	global_load_lds_dwordx4 v160, s[100:101]
	s_add_i32 m0, s36, 0x2000
	s_add_u32 s10, s10, 0x80080
	s_addc_u32 s11, s11, 0
	s_add_i32 s36, s37, s70
	s_add_u32 s100, s10, 0xfff80000
	s_addc_u32 s101, s11, -1
	global_load_lds_dwordx4 v162, s[100:101]
	s_mov_b32 m0, s36
	s_nop 0
	global_load_lds_dwordx4 v160, s[10:11]
	s_add_i32 m0, s36, 0x2000
	s_nop 0
	global_load_lds_dwordx4 v162, s[10:11]
	s_mov_b32 m0, s76
	s_nop 0
	s_add_u32 s100, s62, 0xfff80080
	s_addc_u32 s101, s63, -1
	global_load_lds_dwordx4 v160, s[100:101]
	s_mov_b32 m0, s77
	s_nop 0
	global_load_lds_dwordx4 v162, s[100:101]
	s_waitcnt vmcnt(8)
	s_waitcnt lgkmcnt(0)
	s_barrier
; #define PG8_WAIT_V(n) asm volatile("s_waitcnt vmcnt(" #n ")" ::: "memory")
; #define PG8_WAIT_L(n) asm volatile("s_waitcnt lgkmcnt(" #n ")" ::: "memory")
;     __device__ __forceinline__ void operator()(const f32x4 (&acc)[2][2][4][2], const Unit& u, int wr, int wc, int fr, int fq) const {
;         const int pn = u.pn, r0 = u.pm * BM + wr * 64 + fr;
;         float rstd[2][4];
; #pragma unroll
;         for (int ai = 0; ai < 2; ++ai)
; #pragma unroll
;             for (int m = 0; m < 4; ++m) rstd[ai][m] = (float)ss[r0 + ai * HALF + m * 16] * (1.f / 16777216.f);
;         if (pn < 10) {
; #pragma unroll
;             for (int ai = 0; ai < 2; ++ai) {
;                 f32x4 c[4], s[4];
; #pragma unroll
; template <class Epi, class Sched, bool ALIGN_EPI = false, bool SP2 = false>
; __device__ __forceinline__ void gemm_phase(PG8_LAS unsigned char* lds, const Gemm g, const Sched& S, const Epi& E) {
;     ...
;             PG8_WAIT_V(8); PG8_WAIT_L(0); PG8_BAR; PG8_MMA(1, 0, At, B0); PG8_MMA(1, 1, At, B1); PG8_BAR; PG8_SCHED;
;             } else {
;             PG8_LDB(B0, 0, 0); PG8_SCHED; PG8_LDA(At, 0, 0); PG8_STAGE(PG8_SA(1, 1), a1 + hstep, voffA);
;             PG8_WAIT_L(8); PG8_BAR; PG8_WAIT_L(0); PG8_MMA(0, 0, At, B0); PG8_BAR; PG8_SCHED;
;             PG8_LDB(B1, 0, 1); PG8_STAGE(PG8_SB(0, 0), b2, voffB);
;             PG8_BAR; PG8_WAIT_L(0); PG8_MMA(0, 1, At, B1); PG8_BAR;
;             PG8_LDA(At, 0, 1); PG8_STAGE(PG8_SA(0, 0), a2, voffA);
;             PG8_BAR; PG8_WAIT_L(0); PG8_MMA(1, 0, At, B0); PG8_BAR; PG8_SCHED;
;             PG8_STAGE(PG8_SB(0, 1), b2 + hstep, voffB);
;             PG8_WAIT_V(6); PG8_BAR; PG8_MMA(1, 1, At, B1); PG8_BAR;
;             PG8_LDB(B0, 1, 0); PG8_SCHED; PG8_LDA(At, 1, 0); PG8_STAGE(PG8_SA(0, 1), a2 + hstep, voffA);
;             PG8_WAIT_L(8); PG8_BAR; PG8_WAIT_L(0); PG8_MMA(0, 0, At, B0); PG8_BAR; PG8_SCHED;
;             PG8_LDB(B1, 1, 1); PG8_STAGE(PG8_SB(1, 0), b3, voffB);
;             PG8_BAR; PG8_WAIT_L(0); PG8_MMA(0, 1, At, B1); PG8_BAR;
;             PG8_LDA(At, 1, 1); PG8_STAGE(PG8_SA(1, 0), a3, voffA);
;             PG8_BAR; PG8_WAIT_L(0); PG8_MMA(1, 0, At, B0); PG8_BAR; PG8_SCHED;
;             PG8_STAGE(PG8_SB(1, 1), b3 + hstep, voffB);
;             PG8_WAIT_V(6); PG8_BAR; PG8_MMA(1, 1, At, B1); PG8_BAR;
;             }
;         }
;         if constexpr (ALIGN_EPI) { if (wr == 0) PG8_BAR; }
	s_setprio 1
	s_waitcnt lgkmcnt(0)
	v_mfma_f32_16x16x32_bf16 v[60:63], v[128:131], v[174:177], v[60:63]
	v_mfma_f32_16x16x32_bf16 v[60:63], v[132:135], v[178:181], v[60:63]
	v_mfma_f32_16x16x32_bf16 v[56:59], v[136:139], v[174:177], v[56:59]
	v_mfma_f32_16x16x32_bf16 v[56:59], v[140:143], v[178:181], v[56:59]
	v_mfma_f32_16x16x32_bf16 v[44:47], v[128:131], v[182:185], v[44:47]
	v_mfma_f32_16x16x32_bf16 v[44:47], v[132:135], v[194:197], v[44:47]
	v_mfma_f32_16x16x32_bf16 v[40:43], v[136:139], v[182:185], v[40:43]
	v_mfma_f32_16x16x32_bf16 v[40:43], v[140:143], v[194:197], v[40:43]
	v_mfma_f32_16x16x32_bf16 v[28:31], v[128:131], v[198:201], v[28:31]
	v_mfma_f32_16x16x32_bf16 v[28:31], v[132:135], v[206:209], v[28:31]
	v_mfma_f32_16x16x32_bf16 v[24:27], v[136:139], v[198:201], v[24:27]
	v_mfma_f32_16x16x32_bf16 v[24:27], v[140:143], v[206:209], v[24:27]
	v_mfma_f32_16x16x32_bf16 v[12:15], v[128:131], v[210:213], v[12:15]
	v_mfma_f32_16x16x32_bf16 v[12:15], v[132:135], v[214:217], v[12:15]
	v_mfma_f32_16x16x32_bf16 v[8:11], v[136:139], v[210:213], v[8:11]
	v_mfma_f32_16x16x32_bf16 v[8:11], v[140:143], v[214:217], v[8:11]
	s_setprio 0
	s_setprio 1
	v_mfma_f32_16x16x32_bf16 v[52:55], v[144:147], v[174:177], v[52:55]
	v_mfma_f32_16x16x32_bf16 v[52:55], v[148:151], v[178:181], v[52:55]
	v_mfma_f32_16x16x32_bf16 v[48:51], v[152:155], v[174:177], v[48:51]
	v_mfma_f32_16x16x32_bf16 v[48:51], v[156:159], v[178:181], v[48:51]
	v_mfma_f32_16x16x32_bf16 v[36:39], v[144:147], v[182:185], v[36:39]
	v_mfma_f32_16x16x32_bf16 v[36:39], v[148:151], v[194:197], v[36:39]
	v_mfma_f32_16x16x32_bf16 v[32:35], v[152:155], v[182:185], v[32:35]
	v_mfma_f32_16x16x32_bf16 v[32:35], v[156:159], v[194:197], v[32:35]
	v_mfma_f32_16x16x32_bf16 v[20:23], v[144:147], v[198:201], v[20:23]
	v_mfma_f32_16x16x32_bf16 v[20:23], v[148:151], v[206:209], v[20:23]
	v_mfma_f32_16x16x32_bf16 v[16:19], v[152:155], v[198:201], v[16:19]
	v_mfma_f32_16x16x32_bf16 v[16:19], v[156:159], v[206:209], v[16:19]
	v_mfma_f32_16x16x32_bf16 v[4:7], v[144:147], v[210:213], v[4:7]
	v_mfma_f32_16x16x32_bf16 v[4:7], v[148:151], v[214:217], v[4:7]
	v_mfma_f32_16x16x32_bf16 v[0:3], v[152:155], v[210:213], v[0:3]
	v_mfma_f32_16x16x32_bf16 v[0:3], v[156:159], v[214:217], v[0:3]
	s_setprio 0
	s_barrier
	s_add_i32 s57, s57, 2
	s_add_u32 s8, s8, 0x100
	s_addc_u32 s9, s9, 0
	s_add_u32 s55, s55, 0x100
	s_addc_u32 s3, s3, 0
	s_cmp_gt_u32 s57, 29
	s_cbranch_scc0 .LBB0_344
	s_lshl_b32 s57, s6, 8
	s_add_i32 s57, s57, s75
	v_or_b32_e32 v178, s57, v165
	v_ashrrev_i32_e32 v179, 31, v178
	v_lshl_add_u64 v[128:129], v[178:179], 3, s[92:93]
	global_load_dwordx2 v[130:131], v[128:129], off
	global_load_dwordx2 v[132:133], v[128:129], off offset:128
	global_load_dwordx2 v[134:135], v[128:129], off offset:256
	global_load_dwordx2 v[136:137], v[128:129], off offset:384
	global_load_dwordx2 v[138:139], v[128:129], off offset:1024
	global_load_dwordx2 v[140:141], v[128:129], off offset:1152
	global_load_dwordx2 v[142:143], v[128:129], off offset:1280
	global_load_dwordx2 v[144:145], v[128:129], off offset:1408
	s_and_b64 vcc, exec, s[12:13]
	s_cbranch_vccz .LBB0_347
	s_barrier
.LBB0_347:
	v_or_b32_e32 v194, 16, v178
	v_or_b32_e32 v186, 32, v178
	v_or_b32_e32 v184, 48, v178
	v_add_u32_e32 v182, 0x80, v178
	v_add_u32_e32 v180, 0x90, v178
	v_add_u32_e32 v176, 0xa0, v178
	v_add_u32_e32 v174, 0xb0, v178
	v_ashrrev_i32_e32 v195, 31, v194
	v_ashrrev_i32_e32 v187, 31, v186
	v_ashrrev_i32_e32 v185, 31, v184
	v_ashrrev_i32_e32 v183, 31, v182
	v_ashrrev_i32_e32 v181, 31, v180
	v_ashrrev_i32_e32 v177, 31, v176
	v_ashrrev_i32_e32 v175, 31, v174
	s_mov_b64 s[6:7], -1
	s_cmp_lt_i32 s52, 10
	s_waitcnt vmcnt(7)
	v_ffbh_u32_e32 v146, v131
	v_min_u32_e32 v146, 32, v146
	v_lshlrev_b64 v[130:131], v146, v[130:131]
	v_min_u32_e32 v130, 1, v130
	v_or_b32_e32 v130, v131, v130
	v_cvt_f32_u32_e32 v130, v130
	v_sub_u32_e32 v147, 32, v146
	v_ldexp_f32 v130, v130, v147
	v_mul_f32_e32 v130, 0x33800000, v130
	s_waitcnt vmcnt(6)
	v_ffbh_u32_e32 v146, v133
	v_min_u32_e32 v146, 32, v146
	v_lshlrev_b64 v[132:133], v146, v[132:133]
	v_min_u32_e32 v132, 1, v132
	v_or_b32_e32 v132, v133, v132
	v_cvt_f32_u32_e32 v132, v132
	v_sub_u32_e32 v147, 32, v146
	v_ldexp_f32 v132, v132, v147
	v_mul_f32_e32 v211, 0x33800000, v132
	s_waitcnt vmcnt(5)
	v_ffbh_u32_e32 v146, v135
	v_min_u32_e32 v146, 32, v146
	v_lshlrev_b64 v[134:135], v146, v[134:135]
	v_min_u32_e32 v134, 1, v134
	v_or_b32_e32 v134, v135, v134
	v_cvt_f32_u32_e32 v134, v134
	v_sub_u32_e32 v147, 32, v146
	v_ldexp_f32 v134, v134, v147
	v_mul_f32_e32 v210, 0x33800000, v134
	s_waitcnt vmcnt(4)
	v_ffbh_u32_e32 v146, v137
	v_min_u32_e32 v146, 32, v146
	v_lshlrev_b64 v[136:137], v146, v[136:137]
	v_min_u32_e32 v136, 1, v136
	v_or_b32_e32 v136, v137, v136
	v_cvt_f32_u32_e32 v136, v136
	v_sub_u32_e32 v147, 32, v146
	v_ldexp_f32 v136, v136, v147
	v_mul_f32_e32 v209, 0x33800000, v136
	s_waitcnt vmcnt(3)
	v_ffbh_u32_e32 v146, v139
	v_min_u32_e32 v146, 32, v146
	v_lshlrev_b64 v[138:139], v146, v[138:139]
	v_min_u32_e32 v138, 1, v138
	v_or_b32_e32 v138, v139, v138
	v_cvt_f32_u32_e32 v138, v138
	v_sub_u32_e32 v147, 32, v146
	v_ldexp_f32 v138, v138, v147
	v_mul_f32_e32 v207, 0x33800000, v138
	s_waitcnt vmcnt(2)
	v_ffbh_u32_e32 v146, v141
	v_min_u32_e32 v146, 32, v146
	v_lshlrev_b64 v[140:141], v146, v[140:141]
	v_min_u32_e32 v140, 1, v140
	v_or_b32_e32 v140, v141, v140
	v_cvt_f32_u32_e32 v140, v140
	v_sub_u32_e32 v147, 32, v146
	v_ldexp_f32 v140, v140, v147
	v_mul_f32_e32 v206, 0x33800000, v140
	s_waitcnt vmcnt(1)
	v_ffbh_u32_e32 v146, v143
	v_min_u32_e32 v146, 32, v146
	v_lshlrev_b64 v[142:143], v146, v[142:143]
	v_min_u32_e32 v142, 1, v142
	v_or_b32_e32 v142, v143, v142
	v_cvt_f32_u32_e32 v142, v142
	v_sub_u32_e32 v147, 32, v146
	v_ldexp_f32 v142, v142, v147
	v_mul_f32_e32 v205, 0x33800000, v142
	s_waitcnt vmcnt(0)
	v_ffbh_u32_e32 v146, v145
	v_min_u32_e32 v146, 32, v146
	v_lshlrev_b64 v[144:145], v146, v[144:145]
	v_min_u32_e32 v144, 1, v144
	v_or_b32_e32 v144, v145, v144
	v_cvt_f32_u32_e32 v144, v144
	v_sub_u32_e32 v147, 32, v146
	v_ldexp_f32 v144, v144, v147
	v_mul_f32_e32 v208, 0x33800000, v144
	v_fmamk_f32 v128, v130, 0x3a000000, v227
	v_rsq_f32_e32 v196, v128
	s_cbranch_scc0 .LBB0_350
	s_and_b64 vcc, exec, s[6:7]
	s_cbranch_vccnz .LBB0_415
